# GEMM K-loops: LDS-DMA loads use the lane-offset VGPR directly (no v_mov copy) and form 64-bit bases on SALU instead of two VALU 64-bit adds; + v4
# speedup vs baseline: 1.0171x; 1.0111x over previous
; #define PG8_STAGE(bufoff, gbase, voff) do { _Pragma("unroll") for (int _i = 0; _i < 2; ++_i) \
;         { unsigned vo_ = (voff) + _i * voff##_d; asm volatile("" : "+v"(vo_)); __builtin_amdgcn_global_load_lds((const unsigned*)((const char*)(gbase) + vo_), (PG8_LAS unsigned*)(lds + (bufoff) + ldsw + _i * 8192), 16, 0, 0); } } while (0)
; #define PG8_LDA(dst, b, h) do { _Pragma("unroll") for (int m = 0; m < 4; ++m) _Pragma("unroll") for (int k = 0; k < 2; ++k) dst[m][k] = *(const PG8_LAS bf16x8*)(lds + PG8_SA(b, h) + aoff + m * 2048 + k * 1024); } while (0)
; #define PG8_LDB(dst, b, h) do { _Pragma("unroll") for (int n = 0; n < 2; ++n) _Pragma("unroll") for (int k = 0; k < 2; ++k) dst[n][k] = *(const PG8_LAS bf16x8*)(lds + PG8_SB(b, h) + boff + n * 2048 + k * 1024); } while (0)
; template <class Epi, class Sched, bool ALIGN_EPI, bool F8 = false>
; __device__ __forceinline__ void gemm_phase(PG8_LAS unsigned char* lds, const Gemm g, const Sched& S, const Epi& E, const int wid) {
;     ...
;         for (int t = 0; t < nt; t += 2) {
;             const bool last = (t == nt - 2);
;             const char* a1 = cA + (size_t)(t + 1) * kstep;
;             const char* a2 = last ? nA : cA + (size_t)(t + 2) * kstep; const char* b2 = last ? nB : cB + (size_t)(t + 2) * kstep;
;             const char* a3 = a2 + kstep; const char* b3 = b2 + kstep;
;             PG8_LDB(B0, 0, 0); PG8_LDB(B1, 0, 1); PG8_SCHED; PG8_LDA(At, 0, 0); PG8_STAGE(PG8_SA(1, 1), a1 + hA, voffA);
;             PG8_WAIT_V(8); PG8_WAIT_L(0); PG8_BAR; PG8_MMA(0, 0, At, B0); PG8_MMA(0, 1, At, B1); PG8_BAR; PG8_SCHED;
;             PG8_LDA(At, 0, 1); PG8_STAGE(PG8_SB(0, 0), b2, voffB); PG8_STAGE(PG8_SB(0, 1), b2 + hB, voffB); PG8_STAGE(PG8_SA(0, 0), a2, voffA);
;             PG8_WAIT_V(8); PG8_WAIT_L(0); PG8_BAR; PG8_MMA(1, 0, At, B0); PG8_MMA(1, 1, At, B1); PG8_BAR; PG8_SCHED;
;             PG8_LDB(B0, 1, 0); PG8_LDB(B1, 1, 1); PG8_SCHED; PG8_LDA(At, 1, 0); PG8_STAGE(PG8_SA(0, 1), a2 + hA, voffA);
;             PG8_WAIT_V(8); PG8_WAIT_L(0); PG8_BAR; PG8_MMA(0, 0, At, B0); PG8_MMA(0, 1, At, B1); PG8_BAR; PG8_SCHED;
;             PG8_LDA(At, 1, 1); PG8_STAGE(PG8_SB(1, 0), b3, voffB); PG8_STAGE(PG8_SB(1, 1), b3 + hB, voffB); PG8_STAGE(PG8_SA(1, 0), a3, voffA);
;             PG8_WAIT_V(8); PG8_WAIT_L(0); PG8_BAR; PG8_MMA(1, 0, At, B0); PG8_MMA(1, 1, At, B1); PG8_BAR; PG8_SCHED;
.LBB0_140:
	s_add_i32 s57, s28, 2
	s_add_u32 s30, s26, 0xfffc0080
	s_addc_u32 s29, s27, -1
	s_add_i32 s58, 0, 0x10000
	s_cmp_eq_u32 s49, s28
	s_cselect_b32 s29, s13, s29
	s_cselect_b32 s28, s15, s30
	s_cselect_b32 s31, s53, s56
	s_cselect_b32 s30, s54, s55
	s_add_i32 s60, 0, 0x14000
	v_add_u32_e32 v146, s58, v132
	v_add_u32_e32 v162, s60, v132
	ds_read_b128 v[134:137], v146
	ds_read_b128 v[138:141], v146 offset:1024
	ds_read_b128 v[142:145], v146 offset:2048
	ds_read_b128 v[146:149], v146 offset:3072
	ds_read_b128 v[150:153], v162
	ds_read_b128 v[154:157], v162 offset:1024
	ds_read_b128 v[158:161], v162 offset:2048
	ds_read_b128 v[162:165], v162 offset:3072
	ds_read_b128 v[166:169], v133
	ds_read_b128 v[170:173], v133 offset:1024
	ds_read_b128 v[174:177], v133 offset:2048
	ds_read_b128 v[178:181], v133 offset:3072
	ds_read_b128 v[182:185], v133 offset:4096
	ds_read_b128 v[186:189], v133 offset:5120
	ds_read_b128 v[190:193], v133 offset:6144
	ds_read_b128 v[194:197], v133 offset:7168
	s_add_i32 m0, s25, 0xc000
	s_nop 0
	global_load_lds_dwordx4 v128, s[26:27]
	s_add_i32 m0, s25, 0xe000
	s_nop 0
	global_load_lds_dwordx4 v131, s[26:27]
	s_waitcnt vmcnt(8)
	s_waitcnt lgkmcnt(0)
	s_barrier
	s_setprio 1
	s_waitcnt lgkmcnt(0)
	v_mfma_f32_16x16x128_f8f6f4 v[124:127], v[134:141], v[166:173], v[124:127]
	v_mfma_f32_16x16x128_f8f6f4 v[120:123], v[142:149], v[166:173], v[120:123]
	v_mfma_f32_16x16x128_f8f6f4 v[108:111], v[134:141], v[174:181], v[108:111]
	v_mfma_f32_16x16x128_f8f6f4 v[104:107], v[142:149], v[174:181], v[104:107]
	v_mfma_f32_16x16x128_f8f6f4 v[206:209], v[134:141], v[182:189], v[92:95]
	v_mfma_f32_16x16x128_f8f6f4 v[210:213], v[142:149], v[182:189], v[88:91]
	v_mfma_f32_16x16x128_f8f6f4 v[214:217], v[134:141], v[190:197], v[76:79]
	v_mfma_f32_16x16x128_f8f6f4 v[218:221], v[142:149], v[190:197], v[72:75]
	s_setprio 0
	s_setprio 1
	v_mfma_f32_16x16x128_f8f6f4 v[116:119], v[150:157], v[166:173], v[116:119]
	v_mfma_f32_16x16x128_f8f6f4 v[112:115], v[158:165], v[166:173], v[112:115]
	v_mfma_f32_16x16x128_f8f6f4 v[100:103], v[150:157], v[174:181], v[100:103]
	v_mfma_f32_16x16x128_f8f6f4 v[96:99], v[158:165], v[174:181], v[96:99]
	v_mfma_f32_16x16x128_f8f6f4 v[166:169], v[150:157], v[182:189], v[84:87]
	v_mfma_f32_16x16x128_f8f6f4 v[170:173], v[158:165], v[182:189], v[80:83]
	v_mfma_f32_16x16x128_f8f6f4 v[174:177], v[150:157], v[190:197], v[68:71]
	v_mfma_f32_16x16x128_f8f6f4 v[178:181], v[158:165], v[190:197], v[64:67]
	s_setprio 0
	s_barrier
	s_add_i32 s58, s58, s39
	s_nop 2
	ds_read_b128 v[64:67], v133 offset:16384
	ds_read_b128 v[68:71], v133 offset:17408
	ds_read_b128 v[72:75], v133 offset:18432
	ds_read_b128 v[76:79], v133 offset:19456
	ds_read_b128 v[80:83], v133 offset:20480
	ds_read_b128 v[84:87], v133 offset:21504
	ds_read_b128 v[88:91], v133 offset:22528
	ds_read_b128 v[92:95], v133 offset:23552
	s_mov_b32 m0, s58
	s_nop 0
	global_load_lds_dwordx4 v129, s[30:31]
	s_add_i32 m0, s58, 0x2000
	s_add_u32 s58, s30, 0x40000
	global_load_lds_dwordx4 v130, s[30:31]
	s_addc_u32 s59, s31, 0
	s_add_i32 s60, s60, s39
	s_mov_b32 m0, s60
	s_nop 0
	global_load_lds_dwordx4 v129, s[58:59]
	s_add_i32 m0, s60, 0x2000
	s_nop 0
	global_load_lds_dwordx4 v130, s[58:59]
	s_mov_b32 m0, s25
	s_nop 0
	global_load_lds_dwordx4 v128, s[28:29]
	s_mov_b32 m0, s41
	s_nop 0
	global_load_lds_dwordx4 v131, s[28:29]
	s_waitcnt vmcnt(8)
	s_waitcnt lgkmcnt(0)
	s_barrier
	s_setprio 1
	s_waitcnt lgkmcnt(0)
	v_mfma_f32_16x16x128_f8f6f4 v[60:63], v[134:141], v[64:71], v[60:63]
	v_mfma_f32_16x16x128_f8f6f4 v[56:59], v[142:149], v[64:71], v[56:59]
	v_mfma_f32_16x16x128_f8f6f4 v[182:185], v[134:141], v[72:79], v[44:47]
	v_mfma_f32_16x16x128_f8f6f4 v[186:189], v[142:149], v[72:79], v[40:43]
	v_mfma_f32_16x16x128_f8f6f4 v[190:193], v[134:141], v[80:87], v[28:31]
	v_mfma_f32_16x16x128_f8f6f4 v[194:197], v[142:149], v[80:87], v[24:27]
	v_mfma_f32_16x16x128_f8f6f4 v[242:245], v[134:141], v[88:95], v[12:15]
	v_mfma_f32_16x16x128_f8f6f4 v[246:249], v[142:149], v[88:95], v[8:11]
	s_setprio 0
	s_setprio 1
	v_mfma_f32_16x16x128_f8f6f4 v[52:55], v[150:157], v[64:71], v[52:55]
	v_mfma_f32_16x16x128_f8f6f4 v[48:51], v[158:165], v[64:71], v[48:51]
	v_mfma_f32_16x16x128_f8f6f4 v[250:253], v[150:157], v[72:79], v[36:39]
	v_mfma_f32_16x16x128_f8f6f4 v[228:231], v[158:165], v[72:79], v[32:35]
	v_mfma_f32_16x16x128_f8f6f4 v[202:205], v[150:157], v[80:87], v[20:23]
	v_mfma_f32_16x16x128_f8f6f4 v[236:239], v[158:165], v[80:87], v[16:19]
	v_mfma_f32_16x16x128_f8f6f4 v[224:227], v[150:157], v[88:95], v[4:7]
	v_mfma_f32_16x16x128_f8f6f4 v[232:235], v[158:165], v[88:95], v[0:3]
	s_setprio 0
	s_barrier
; #define PG8_STAGE(bufoff, gbase, voff) do { _Pragma("unroll") for (int _i = 0; _i < 2; ++_i) \
;         { unsigned vo_ = (voff) + _i * voff##_d; asm volatile("" : "+v"(vo_)); __builtin_amdgcn_global_load_lds((const unsigned*)((const char*)(gbase) + vo_), (PG8_LAS unsigned*)(lds + (bufoff) + ldsw + _i * 8192), 16, 0, 0); } } while (0)
; #define PG8_LDA(dst, b, h) do { _Pragma("unroll") for (int m = 0; m < 4; ++m) _Pragma("unroll") for (int k = 0; k < 2; ++k) dst[m][k] = *(const PG8_LAS bf16x8*)(lds + PG8_SA(b, h) + aoff + m * 2048 + k * 1024); } while (0)
; #define PG8_LDB(dst, b, h) do { _Pragma("unroll") for (int n = 0; n < 2; ++n) _Pragma("unroll") for (int k = 0; k < 2; ++k) dst[n][k] = *(const PG8_LAS bf16x8*)(lds + PG8_SB(b, h) + boff + n * 2048 + k * 1024); } while (0)
; template <class Epi, class Sched, bool ALIGN_EPI, bool F8 = false>
; __device__ __forceinline__ void gemm_phase(PG8_LAS unsigned char* lds, const Gemm g, const Sched& S, const Epi& E, const int wid) {
;     ...
;         for (int t = 0; t < nt; t += 2) {
;             const bool last = (t == nt - 2);
;             const char* a1 = cA + (size_t)(t + 1) * kstep;
;             const char* a2 = last ? nA : cA + (size_t)(t + 2) * kstep; const char* b2 = last ? nB : cB + (size_t)(t + 2) * kstep;
;             const char* a3 = a2 + kstep; const char* b3 = b2 + kstep;
;             PG8_LDB(B0, 0, 0); PG8_LDB(B1, 0, 1); PG8_SCHED; PG8_LDA(At, 0, 0); PG8_STAGE(PG8_SA(1, 1), a1 + hA, voffA);
;             PG8_WAIT_V(8); PG8_WAIT_L(0); PG8_BAR; PG8_MMA(0, 0, At, B0); PG8_MMA(0, 1, At, B1); PG8_BAR; PG8_SCHED;
;             PG8_LDA(At, 0, 1); PG8_STAGE(PG8_SB(0, 0), b2, voffB); PG8_STAGE(PG8_SB(0, 1), b2 + hB, voffB); PG8_STAGE(PG8_SA(0, 0), a2, voffA);
;             PG8_WAIT_V(8); PG8_WAIT_L(0); PG8_BAR; PG8_MMA(1, 0, At, B0); PG8_MMA(1, 1, At, B1); PG8_BAR; PG8_SCHED;
;             PG8_LDB(B0, 1, 0); PG8_LDB(B1, 1, 1); PG8_SCHED; PG8_LDA(At, 1, 0); PG8_STAGE(PG8_SA(0, 1), a2 + hA, voffA);
;             PG8_WAIT_V(8); PG8_WAIT_L(0); PG8_BAR; PG8_MMA(0, 0, At, B0); PG8_MMA(0, 1, At, B1); PG8_BAR; PG8_SCHED;
;             PG8_LDA(At, 1, 1); PG8_STAGE(PG8_SB(1, 0), b3, voffB); PG8_STAGE(PG8_SB(1, 1), b3 + hB, voffB); PG8_STAGE(PG8_SA(1, 0), a3, voffA);
;             PG8_WAIT_V(8); PG8_WAIT_L(0); PG8_BAR; PG8_MMA(1, 0, At, B0); PG8_MMA(1, 1, At, B1); PG8_BAR; PG8_SCHED;
	s_add_i32 s60, 0, 0x18000
	v_add_u32_e32 v8, s60, v132
	s_add_i32 s61, 0, 0x1c000
	s_nop 1
	ds_read_b128 v[0:3], v8
	ds_read_b128 v[4:7], v8 offset:1024
	ds_read_b128 v[16:19], v8 offset:2048
	ds_read_b128 v[20:23], v8 offset:3072
	v_add_u32_e32 v8, s61, v132
	ds_read_b128 v[134:137], v8
	ds_read_b128 v[138:141], v8 offset:1024
	ds_read_b128 v[142:145], v8 offset:2048
	ds_read_b128 v[146:149], v8 offset:3072
	s_add_u32 s58, s28, 0x40000
	s_mov_b32 m0, s42
	ds_read_b128 v[8:11], v133 offset:32768
	ds_read_b128 v[12:15], v133 offset:33792
	ds_read_b128 v[24:27], v133 offset:34816
	ds_read_b128 v[28:31], v133 offset:35840
	ds_read_b128 v[32:35], v133 offset:36864
	ds_read_b128 v[36:39], v133 offset:37888
	ds_read_b128 v[40:43], v133 offset:38912
	ds_read_b128 v[44:47], v133 offset:39936
	s_addc_u32 s59, s29, 0
	s_nop 0
	global_load_lds_dwordx4 v128, s[58:59]
	s_mov_b32 m0, s43
	s_nop 0
	global_load_lds_dwordx4 v131, s[58:59]
	s_waitcnt vmcnt(8)
	s_waitcnt lgkmcnt(0)
	s_barrier
	s_setprio 1
	s_waitcnt lgkmcnt(0)
	v_mfma_f32_16x16x128_f8f6f4 v[124:127], v[0:7], v[8:15], v[124:127]
	v_mfma_f32_16x16x128_f8f6f4 v[120:123], v[16:23], v[8:15], v[120:123]
	v_mfma_f32_16x16x128_f8f6f4 v[108:111], v[0:7], v[24:31], v[108:111]
	v_mfma_f32_16x16x128_f8f6f4 v[104:107], v[16:23], v[24:31], v[104:107]
	v_mfma_f32_16x16x128_f8f6f4 v[92:95], v[0:7], v[32:39], v[206:209]
	v_mfma_f32_16x16x128_f8f6f4 v[88:91], v[16:23], v[32:39], v[210:213]
	v_mfma_f32_16x16x128_f8f6f4 v[76:79], v[0:7], v[40:47], v[214:217]
	v_mfma_f32_16x16x128_f8f6f4 v[72:75], v[16:23], v[40:47], v[218:221]
	s_setprio 0
	s_setprio 1
	v_mfma_f32_16x16x128_f8f6f4 v[116:119], v[134:141], v[8:15], v[116:119]
	v_mfma_f32_16x16x128_f8f6f4 v[112:115], v[142:149], v[8:15], v[112:115]
	v_mfma_f32_16x16x128_f8f6f4 v[100:103], v[134:141], v[24:31], v[100:103]
	v_mfma_f32_16x16x128_f8f6f4 v[96:99], v[142:149], v[24:31], v[96:99]
	v_mfma_f32_16x16x128_f8f6f4 v[84:87], v[134:141], v[32:39], v[166:169]
	v_mfma_f32_16x16x128_f8f6f4 v[80:83], v[142:149], v[32:39], v[170:173]
	v_mfma_f32_16x16x128_f8f6f4 v[68:71], v[134:141], v[40:47], v[174:177]
	v_mfma_f32_16x16x128_f8f6f4 v[64:67], v[142:149], v[40:47], v[178:181]
	s_setprio 0
	s_barrier
	ds_read_b128 v[32:35], v133 offset:49152
	ds_read_b128 v[36:39], v133 offset:50176
	ds_read_b128 v[150:153], v133 offset:51200
	ds_read_b128 v[154:157], v133 offset:52224
	ds_read_b128 v[158:161], v133 offset:53248
	ds_read_b128 v[162:165], v133 offset:54272
	ds_read_b128 v[166:169], v133 offset:55296
	ds_read_b128 v[170:173], v133 offset:56320
	s_add_i32 s58, s60, s39
	s_add_u32 s100, s30, s2
	s_addc_u32 s101, s31, s3
	s_mov_b32 m0, s58
	s_nop 0
	global_load_lds_dwordx4 v129, s[100:101]
	s_add_i32 m0, s58, 0x2000
	s_add_u32 s100, s30, s2
	s_addc_u32 s101, s31, s3
	s_add_u32 s30, s30, 0x40080
	global_load_lds_dwordx4 v130, s[100:101]
	s_addc_u32 s31, s31, 0
	s_add_i32 s58, s61, s39
	s_mov_b32 m0, s58
	s_nop 0
	global_load_lds_dwordx4 v129, s[30:31]
	s_add_i32 m0, s58, 0x2000
	s_nop 0
	global_load_lds_dwordx4 v130, s[30:31]
	s_mov_b32 m0, s47
	s_add_u32 s100, s28, s2
	s_addc_u32 s101, s29, s3
	global_load_lds_dwordx4 v128, s[100:101]
	s_mov_b32 m0, s48
	s_add_u32 s100, s28, s2
	s_addc_u32 s101, s29, s3
	global_load_lds_dwordx4 v131, s[100:101]
	s_waitcnt vmcnt(8)
	s_waitcnt lgkmcnt(0)
	s_barrier
	s_setprio 1
	s_waitcnt lgkmcnt(0)
	v_mfma_f32_16x16x128_f8f6f4 v[60:63], v[0:7], v[32:39], v[60:63]
	v_mfma_f32_16x16x128_f8f6f4 v[56:59], v[16:23], v[32:39], v[56:59]
	v_mfma_f32_16x16x128_f8f6f4 v[44:47], v[0:7], v[150:157], v[182:185]
	v_mfma_f32_16x16x128_f8f6f4 v[40:43], v[16:23], v[150:157], v[186:189]
	v_mfma_f32_16x16x128_f8f6f4 v[28:31], v[0:7], v[158:165], v[190:193]
	v_mfma_f32_16x16x128_f8f6f4 v[24:27], v[16:23], v[158:165], v[194:197]
	v_mfma_f32_16x16x128_f8f6f4 v[12:15], v[0:7], v[166:173], v[242:245]
	v_mfma_f32_16x16x128_f8f6f4 v[8:11], v[16:23], v[166:173], v[246:249]
	s_setprio 0
	s_setprio 1
	v_mfma_f32_16x16x128_f8f6f4 v[52:55], v[134:141], v[32:39], v[52:55]
	v_mfma_f32_16x16x128_f8f6f4 v[48:51], v[142:149], v[32:39], v[48:51]
	v_mfma_f32_16x16x128_f8f6f4 v[36:39], v[134:141], v[150:157], v[250:253]
	v_mfma_f32_16x16x128_f8f6f4 v[32:35], v[142:149], v[150:157], v[228:231]
	v_mfma_f32_16x16x128_f8f6f4 v[20:23], v[134:141], v[158:165], v[202:205]
	v_mfma_f32_16x16x128_f8f6f4 v[16:19], v[142:149], v[158:165], v[236:239]
	v_mfma_f32_16x16x128_f8f6f4 v[4:7], v[134:141], v[166:173], v[224:227]
	v_mfma_f32_16x16x128_f8f6f4 v[0:3], v[142:149], v[166:173], v[232:235]
	s_setprio 0
	s_barrier
	s_add_u32 s26, s26, 0x100
	s_addc_u32 s27, s27, 0
	s_add_u32 s55, s55, 0x100
	s_addc_u32 s56, s56, 0
	s_cmp_ge_i32 s57, s44
	s_mov_b32 s28, s57
	s_cbranch_scc0 .LBB0_140
	v_mov_b32_e32 v232, v199
	v_mov_b32_e32 v233, v223
	v_mov_b32_e32 v223, 0x260
	v_mov_b32_e32 v234, 0x1e000
	v_mov_b32_e32 v235, 0x7f800000
	v_mov_b32_e32 v236, 0x7fc00000
	v_mov_b32_e32 v237, 0x7fffff
	v_mov_b64_e32 v[238:239], 0x140
	v_mov_b64_e32 v[252:253], 0x13f

; #define PG8_STAGE(bufoff, gbase, voff) do { _Pragma("unroll") for (int _i = 0; _i < 2; ++_i) \
;         { unsigned vo_ = (voff) + _i * voff##_d; asm volatile("" : "+v"(vo_)); __builtin_amdgcn_global_load_lds((const unsigned*)((const char*)(gbase) + vo_), (PG8_LAS unsigned*)(lds + (bufoff) + ldsw + _i * 8192), 16, 0, 0); } } while (0)
; #define PG8_LDA(dst, b, h) do { _Pragma("unroll") for (int m = 0; m < 4; ++m) _Pragma("unroll") for (int k = 0; k < 2; ++k) dst[m][k] = *(const PG8_LAS bf16x8*)(lds + PG8_SA(b, h) + aoff + m * 2048 + k * 1024); } while (0)
; #define PG8_LDB(dst, b, h) do { _Pragma("unroll") for (int n = 0; n < 2; ++n) _Pragma("unroll") for (int k = 0; k < 2; ++k) dst[n][k] = *(const PG8_LAS bf16x8*)(lds + PG8_SB(b, h) + boff + n * 2048 + k * 1024); } while (0)
; template <class Epi, class Sched, bool ALIGN_EPI, bool F8 = false>
; __device__ __forceinline__ void gemm_phase(PG8_LAS unsigned char* lds, const Gemm g, const Sched& S, const Epi& E, const int wid) {
;     ...
;         for (int t = 0; t < nt; t += 2) {
;             const bool last = (t == nt - 2);
;             const char* a1 = cA + (size_t)(t + 1) * kstep;
;             const char* a2 = last ? nA : cA + (size_t)(t + 2) * kstep; const char* b2 = last ? nB : cB + (size_t)(t + 2) * kstep;
;             const char* a3 = a2 + kstep; const char* b3 = b2 + kstep;
;             PG8_LDB(B0, 0, 0); PG8_LDB(B1, 0, 1); PG8_SCHED; PG8_LDA(At, 0, 0); PG8_STAGE(PG8_SA(1, 1), a1 + hA, voffA);
;             PG8_WAIT_V(8); PG8_WAIT_L(0); PG8_BAR; PG8_MMA(0, 0, At, B0); PG8_MMA(0, 1, At, B1); PG8_BAR; PG8_SCHED;
;             PG8_LDA(At, 0, 1); PG8_STAGE(PG8_SB(0, 0), b2, voffB); PG8_STAGE(PG8_SB(0, 1), b2 + hB, voffB); PG8_STAGE(PG8_SA(0, 0), a2, voffA);
;             PG8_WAIT_V(8); PG8_WAIT_L(0); PG8_BAR; PG8_MMA(1, 0, At, B0); PG8_MMA(1, 1, At, B1); PG8_BAR; PG8_SCHED;
;             PG8_LDB(B0, 1, 0); PG8_LDB(B1, 1, 1); PG8_SCHED; PG8_LDA(At, 1, 0); PG8_STAGE(PG8_SA(0, 1), a2 + hA, voffA);
;             PG8_WAIT_V(8); PG8_WAIT_L(0); PG8_BAR; PG8_MMA(0, 0, At, B0); PG8_MMA(0, 1, At, B1); PG8_BAR; PG8_SCHED;
;             PG8_LDA(At, 1, 1); PG8_STAGE(PG8_SB(1, 0), b3, voffB); PG8_STAGE(PG8_SB(1, 1), b3 + hB, voffB); PG8_STAGE(PG8_SA(1, 0), a3, voffA);
;             PG8_WAIT_V(8); PG8_WAIT_L(0); PG8_BAR; PG8_MMA(1, 0, At, B0); PG8_MMA(1, 1, At, B1); PG8_BAR; PG8_SCHED;
.LBB0_160:
	s_add_i32 s59, s10, 2
	s_add_u32 s8, s6, 0xfff80080
	s_addc_u32 s9, s7, -1
	s_add_i32 s61, 0, 0x10000
	s_cmp_eq_u32 s89, s10
	s_cselect_b32 s9, s1, s9
	s_cselect_b32 s8, s12, s8
	s_cselect_b32 s11, s13, s33
	s_cselect_b32 s10, s14, s15
	s_add_i32 s94, 0, 0x14000
	v_add_u32_e32 v140, s61, v219
	v_add_u32_e32 v156, s94, v219
	ds_read_b128 v[128:131], v140
	ds_read_b128 v[132:135], v140 offset:1024
	ds_read_b128 v[136:139], v140 offset:2048
	ds_read_b128 v[140:143], v140 offset:3072
	ds_read_b128 v[144:147], v156
	ds_read_b128 v[148:151], v156 offset:1024
	ds_read_b128 v[152:155], v156 offset:2048
	ds_read_b128 v[156:159], v156 offset:3072
	ds_read_b128 v[160:163], v220
	ds_read_b128 v[164:167], v220 offset:1024
	ds_read_b128 v[168:171], v220 offset:2048
	ds_read_b128 v[172:175], v220 offset:3072
	ds_read_b128 v[176:179], v220 offset:4096
	ds_read_b128 v[180:183], v220 offset:5120
	ds_read_b128 v[184:187], v220 offset:6144
	ds_read_b128 v[188:191], v220 offset:7168
	s_add_i32 m0, s80, 0xc000
	s_nop 0
	global_load_lds_dwordx4 v217, s[6:7]
	s_add_i32 m0, s80, 0xe000
	s_nop 0
	global_load_lds_dwordx4 v218, s[6:7]
	s_waitcnt vmcnt(8)
	s_waitcnt lgkmcnt(0)
	s_barrier
	s_setprio 1
	s_waitcnt lgkmcnt(0)
	v_mfma_f32_16x16x32_bf16 v[124:127], v[128:131], v[160:163], v[124:127]
	v_mfma_f32_16x16x32_bf16 v[116:119], v[136:139], v[160:163], v[116:119]
	v_mfma_f32_16x16x32_bf16 v[108:111], v[128:131], v[168:171], v[108:111]
	v_mfma_f32_16x16x32_bf16 v[104:107], v[136:139], v[168:171], v[104:107]
	v_mfma_f32_16x16x32_bf16 v[92:95], v[128:131], v[176:179], v[92:95]
	v_mfma_f32_16x16x32_bf16 v[88:91], v[136:139], v[176:179], v[88:91]
	v_mfma_f32_16x16x32_bf16 v[76:79], v[128:131], v[184:187], v[76:79]
	v_mfma_f32_16x16x32_bf16 v[72:75], v[136:139], v[184:187], v[72:75]
	v_mfma_f32_16x16x32_bf16 v[124:127], v[132:135], v[164:167], v[124:127]
	v_mfma_f32_16x16x32_bf16 v[116:119], v[140:143], v[164:167], v[116:119]
	v_mfma_f32_16x16x32_bf16 v[108:111], v[132:135], v[172:175], v[108:111]
	v_mfma_f32_16x16x32_bf16 v[104:107], v[140:143], v[172:175], v[104:107]
	v_mfma_f32_16x16x32_bf16 v[92:95], v[132:135], v[180:183], v[92:95]
	v_mfma_f32_16x16x32_bf16 v[88:91], v[140:143], v[180:183], v[88:91]
	v_mfma_f32_16x16x32_bf16 v[76:79], v[132:135], v[188:191], v[76:79]
	v_mfma_f32_16x16x32_bf16 v[72:75], v[140:143], v[188:191], v[72:75]
	s_setprio 0
	s_setprio 1
	v_mfma_f32_16x16x32_bf16 v[120:123], v[144:147], v[160:163], v[120:123]
	v_mfma_f32_16x16x32_bf16 v[112:115], v[152:155], v[160:163], v[112:115]
	v_mfma_f32_16x16x32_bf16 v[100:103], v[144:147], v[168:171], v[100:103]
	v_mfma_f32_16x16x32_bf16 v[96:99], v[152:155], v[168:171], v[96:99]
	v_mfma_f32_16x16x32_bf16 v[84:87], v[144:147], v[176:179], v[84:87]
	v_mfma_f32_16x16x32_bf16 v[80:83], v[152:155], v[176:179], v[80:83]
	v_mfma_f32_16x16x32_bf16 v[68:71], v[144:147], v[184:187], v[68:71]
	v_mfma_f32_16x16x32_bf16 v[64:67], v[152:155], v[184:187], v[64:67]
	v_mfma_f32_16x16x32_bf16 v[120:123], v[148:151], v[164:167], v[120:123]
	v_mfma_f32_16x16x32_bf16 v[112:115], v[156:159], v[164:167], v[112:115]
	v_mfma_f32_16x16x32_bf16 v[100:103], v[148:151], v[172:175], v[100:103]
	v_mfma_f32_16x16x32_bf16 v[96:99], v[156:159], v[172:175], v[96:99]
	v_mfma_f32_16x16x32_bf16 v[84:87], v[148:151], v[180:183], v[84:87]
	v_mfma_f32_16x16x32_bf16 v[80:83], v[156:159], v[180:183], v[80:83]
	v_mfma_f32_16x16x32_bf16 v[68:71], v[148:151], v[188:191], v[68:71]
	v_mfma_f32_16x16x32_bf16 v[64:67], v[156:159], v[188:191], v[64:67]
	s_setprio 0
	s_barrier
	s_add_i32 s61, s61, s79
	ds_read_b128 v[160:163], v220 offset:16384
	ds_read_b128 v[164:167], v220 offset:17408
	ds_read_b128 v[168:171], v220 offset:18432
	ds_read_b128 v[172:175], v220 offset:19456
	ds_read_b128 v[176:179], v220 offset:20480
	ds_read_b128 v[180:183], v220 offset:21504
	ds_read_b128 v[184:187], v220 offset:22528
	ds_read_b128 v[188:191], v220 offset:23552
	s_mov_b32 m0, s61
	s_nop 0
	global_load_lds_dwordx4 v217, s[10:11]
	s_add_i32 m0, s61, 0x2000
	s_add_u32 s70, s10, 0x80000
	global_load_lds_dwordx4 v218, s[10:11]
	s_addc_u32 s71, s11, 0
	s_add_i32 s61, s94, s79
	s_mov_b32 m0, s61
	s_nop 0
	global_load_lds_dwordx4 v217, s[70:71]
	s_add_i32 m0, s61, 0x2000
	s_nop 0
	global_load_lds_dwordx4 v218, s[70:71]
	s_mov_b32 m0, s80
	s_nop 0
	global_load_lds_dwordx4 v217, s[8:9]
	s_mov_b32 m0, s81
	s_nop 0
	global_load_lds_dwordx4 v218, s[8:9]
	s_waitcnt vmcnt(8)
	s_waitcnt lgkmcnt(0)
	s_barrier
	s_setprio 1
	s_waitcnt lgkmcnt(0)
	v_mfma_f32_16x16x32_bf16 v[60:63], v[128:131], v[160:163], v[60:63]
	v_mfma_f32_16x16x32_bf16 v[56:59], v[136:139], v[160:163], v[56:59]
	v_mfma_f32_16x16x32_bf16 v[44:47], v[128:131], v[168:171], v[44:47]
	v_mfma_f32_16x16x32_bf16 v[40:43], v[136:139], v[168:171], v[40:43]
	v_mfma_f32_16x16x32_bf16 v[28:31], v[128:131], v[176:179], v[28:31]
	v_mfma_f32_16x16x32_bf16 v[24:27], v[136:139], v[176:179], v[24:27]
	v_mfma_f32_16x16x32_bf16 v[12:15], v[128:131], v[184:187], v[12:15]
	v_mfma_f32_16x16x32_bf16 v[8:11], v[136:139], v[184:187], v[8:11]
	v_mfma_f32_16x16x32_bf16 v[60:63], v[132:135], v[164:167], v[60:63]
	v_mfma_f32_16x16x32_bf16 v[56:59], v[140:143], v[164:167], v[56:59]
	v_mfma_f32_16x16x32_bf16 v[44:47], v[132:135], v[172:175], v[44:47]
	v_mfma_f32_16x16x32_bf16 v[40:43], v[140:143], v[172:175], v[40:43]
	v_mfma_f32_16x16x32_bf16 v[28:31], v[132:135], v[180:183], v[28:31]
	v_mfma_f32_16x16x32_bf16 v[24:27], v[140:143], v[180:183], v[24:27]
	v_mfma_f32_16x16x32_bf16 v[12:15], v[132:135], v[188:191], v[12:15]
	v_mfma_f32_16x16x32_bf16 v[8:11], v[140:143], v[188:191], v[8:11]
	s_setprio 0
	s_setprio 1
	v_mfma_f32_16x16x32_bf16 v[52:55], v[144:147], v[160:163], v[52:55]
	v_mfma_f32_16x16x32_bf16 v[48:51], v[152:155], v[160:163], v[48:51]
	v_mfma_f32_16x16x32_bf16 v[36:39], v[144:147], v[168:171], v[36:39]
	v_mfma_f32_16x16x32_bf16 v[32:35], v[152:155], v[168:171], v[32:35]
	v_mfma_f32_16x16x32_bf16 v[20:23], v[144:147], v[176:179], v[20:23]
	v_mfma_f32_16x16x32_bf16 v[16:19], v[152:155], v[176:179], v[16:19]
	v_mfma_f32_16x16x32_bf16 v[4:7], v[144:147], v[184:187], v[4:7]
	v_mfma_f32_16x16x32_bf16 v[0:3], v[152:155], v[184:187], v[0:3]
	v_mfma_f32_16x16x32_bf16 v[52:55], v[148:151], v[164:167], v[52:55]
	v_mfma_f32_16x16x32_bf16 v[48:51], v[156:159], v[164:167], v[48:51]
	v_mfma_f32_16x16x32_bf16 v[36:39], v[148:151], v[172:175], v[36:39]
	v_mfma_f32_16x16x32_bf16 v[32:35], v[156:159], v[172:175], v[32:35]
	v_mfma_f32_16x16x32_bf16 v[20:23], v[148:151], v[180:183], v[20:23]
	v_mfma_f32_16x16x32_bf16 v[16:19], v[156:159], v[180:183], v[16:19]
	v_mfma_f32_16x16x32_bf16 v[4:7], v[148:151], v[188:191], v[4:7]
	v_mfma_f32_16x16x32_bf16 v[0:3], v[156:159], v[188:191], v[0:3]
	s_setprio 0
	s_barrier
; #define PG8_STAGE(bufoff, gbase, voff) do { _Pragma("unroll") for (int _i = 0; _i < 2; ++_i) \
;         { unsigned vo_ = (voff) + _i * voff##_d; asm volatile("" : "+v"(vo_)); __builtin_amdgcn_global_load_lds((const unsigned*)((const char*)(gbase) + vo_), (PG8_LAS unsigned*)(lds + (bufoff) + ldsw + _i * 8192), 16, 0, 0); } } while (0)
; #define PG8_LDA(dst, b, h) do { _Pragma("unroll") for (int m = 0; m < 4; ++m) _Pragma("unroll") for (int k = 0; k < 2; ++k) dst[m][k] = *(const PG8_LAS bf16x8*)(lds + PG8_SA(b, h) + aoff + m * 2048 + k * 1024); } while (0)
; #define PG8_LDB(dst, b, h) do { _Pragma("unroll") for (int n = 0; n < 2; ++n) _Pragma("unroll") for (int k = 0; k < 2; ++k) dst[n][k] = *(const PG8_LAS bf16x8*)(lds + PG8_SB(b, h) + boff + n * 2048 + k * 1024); } while (0)
; template <class Epi, class Sched, bool ALIGN_EPI, bool F8 = false>
; __device__ __forceinline__ void gemm_phase(PG8_LAS unsigned char* lds, const Gemm g, const Sched& S, const Epi& E, const int wid) {
;     ...
;         for (int t = 0; t < nt; t += 2) {
;             const bool last = (t == nt - 2);
;             const char* a1 = cA + (size_t)(t + 1) * kstep;
;             const char* a2 = last ? nA : cA + (size_t)(t + 2) * kstep; const char* b2 = last ? nB : cB + (size_t)(t + 2) * kstep;
;             const char* a3 = a2 + kstep; const char* b3 = b2 + kstep;
;             PG8_LDB(B0, 0, 0); PG8_LDB(B1, 0, 1); PG8_SCHED; PG8_LDA(At, 0, 0); PG8_STAGE(PG8_SA(1, 1), a1 + hA, voffA);
;             PG8_WAIT_V(8); PG8_WAIT_L(0); PG8_BAR; PG8_MMA(0, 0, At, B0); PG8_MMA(0, 1, At, B1); PG8_BAR; PG8_SCHED;
;             PG8_LDA(At, 0, 1); PG8_STAGE(PG8_SB(0, 0), b2, voffB); PG8_STAGE(PG8_SB(0, 1), b2 + hB, voffB); PG8_STAGE(PG8_SA(0, 0), a2, voffA);
;             PG8_WAIT_V(8); PG8_WAIT_L(0); PG8_BAR; PG8_MMA(1, 0, At, B0); PG8_MMA(1, 1, At, B1); PG8_BAR; PG8_SCHED;
;             PG8_LDB(B0, 1, 0); PG8_LDB(B1, 1, 1); PG8_SCHED; PG8_LDA(At, 1, 0); PG8_STAGE(PG8_SA(0, 1), a2 + hA, voffA);
;             PG8_WAIT_V(8); PG8_WAIT_L(0); PG8_BAR; PG8_MMA(0, 0, At, B0); PG8_MMA(0, 1, At, B1); PG8_BAR; PG8_SCHED;
;             PG8_LDA(At, 1, 1); PG8_STAGE(PG8_SB(1, 0), b3, voffB); PG8_STAGE(PG8_SB(1, 1), b3 + hB, voffB); PG8_STAGE(PG8_SA(1, 0), a3, voffA);
;             PG8_WAIT_V(8); PG8_WAIT_L(0); PG8_BAR; PG8_MMA(1, 0, At, B0); PG8_MMA(1, 1, At, B1); PG8_BAR; PG8_SCHED;
	s_add_i32 s61, 0, 0x18000
	s_add_i32 s94, 0, 0x1c000
	v_add_u32_e32 v140, s61, v219
	v_add_u32_e32 v156, s94, v219
	ds_read_b128 v[128:131], v140
	ds_read_b128 v[132:135], v140 offset:1024
	ds_read_b128 v[136:139], v140 offset:2048
	ds_read_b128 v[140:143], v140 offset:3072
	ds_read_b128 v[144:147], v156
	ds_read_b128 v[148:151], v156 offset:1024
	ds_read_b128 v[152:155], v156 offset:2048
	ds_read_b128 v[156:159], v156 offset:3072
	s_add_u32 s70, s8, 0x80000
	s_mov_b32 m0, s82
	ds_read_b128 v[160:163], v220 offset:32768
	ds_read_b128 v[164:167], v220 offset:33792
	ds_read_b128 v[168:171], v220 offset:34816
	ds_read_b128 v[172:175], v220 offset:35840
	ds_read_b128 v[176:179], v220 offset:36864
	ds_read_b128 v[180:183], v220 offset:37888
	ds_read_b128 v[184:187], v220 offset:38912
	ds_read_b128 v[188:191], v220 offset:39936
	s_addc_u32 s71, s9, 0
	s_nop 0
	global_load_lds_dwordx4 v217, s[70:71]
	s_mov_b32 m0, s83
	s_nop 0
	global_load_lds_dwordx4 v218, s[70:71]
	s_waitcnt vmcnt(8)
	s_waitcnt lgkmcnt(0)
	s_barrier
	s_setprio 1
	s_waitcnt lgkmcnt(0)
	v_mfma_f32_16x16x32_bf16 v[124:127], v[128:131], v[160:163], v[124:127]
	v_mfma_f32_16x16x32_bf16 v[116:119], v[136:139], v[160:163], v[116:119]
	v_mfma_f32_16x16x32_bf16 v[108:111], v[128:131], v[168:171], v[108:111]
	v_mfma_f32_16x16x32_bf16 v[104:107], v[136:139], v[168:171], v[104:107]
	v_mfma_f32_16x16x32_bf16 v[92:95], v[128:131], v[176:179], v[92:95]
	v_mfma_f32_16x16x32_bf16 v[88:91], v[136:139], v[176:179], v[88:91]
	v_mfma_f32_16x16x32_bf16 v[76:79], v[128:131], v[184:187], v[76:79]
	v_mfma_f32_16x16x32_bf16 v[72:75], v[136:139], v[184:187], v[72:75]
	v_mfma_f32_16x16x32_bf16 v[124:127], v[132:135], v[164:167], v[124:127]
	v_mfma_f32_16x16x32_bf16 v[116:119], v[140:143], v[164:167], v[116:119]
	v_mfma_f32_16x16x32_bf16 v[108:111], v[132:135], v[172:175], v[108:111]
	v_mfma_f32_16x16x32_bf16 v[104:107], v[140:143], v[172:175], v[104:107]
	v_mfma_f32_16x16x32_bf16 v[92:95], v[132:135], v[180:183], v[92:95]
	v_mfma_f32_16x16x32_bf16 v[88:91], v[140:143], v[180:183], v[88:91]
	v_mfma_f32_16x16x32_bf16 v[76:79], v[132:135], v[188:191], v[76:79]
	v_mfma_f32_16x16x32_bf16 v[72:75], v[140:143], v[188:191], v[72:75]
	s_setprio 0
	s_setprio 1
	v_mfma_f32_16x16x32_bf16 v[120:123], v[144:147], v[160:163], v[120:123]
	v_mfma_f32_16x16x32_bf16 v[112:115], v[152:155], v[160:163], v[112:115]
	v_mfma_f32_16x16x32_bf16 v[100:103], v[144:147], v[168:171], v[100:103]
	v_mfma_f32_16x16x32_bf16 v[96:99], v[152:155], v[168:171], v[96:99]
	v_mfma_f32_16x16x32_bf16 v[84:87], v[144:147], v[176:179], v[84:87]
	v_mfma_f32_16x16x32_bf16 v[80:83], v[152:155], v[176:179], v[80:83]
	v_mfma_f32_16x16x32_bf16 v[68:71], v[144:147], v[184:187], v[68:71]
	v_mfma_f32_16x16x32_bf16 v[64:67], v[152:155], v[184:187], v[64:67]
	v_mfma_f32_16x16x32_bf16 v[120:123], v[148:151], v[164:167], v[120:123]
	v_mfma_f32_16x16x32_bf16 v[112:115], v[156:159], v[164:167], v[112:115]
	v_mfma_f32_16x16x32_bf16 v[100:103], v[148:151], v[172:175], v[100:103]
	v_mfma_f32_16x16x32_bf16 v[96:99], v[156:159], v[172:175], v[96:99]
	v_mfma_f32_16x16x32_bf16 v[84:87], v[148:151], v[180:183], v[84:87]
	v_mfma_f32_16x16x32_bf16 v[80:83], v[156:159], v[180:183], v[80:83]
	v_mfma_f32_16x16x32_bf16 v[68:71], v[148:151], v[188:191], v[68:71]
	v_mfma_f32_16x16x32_bf16 v[64:67], v[156:159], v[188:191], v[64:67]
	s_setprio 0
	s_barrier
; #define PG8_STAGE(bufoff, gbase, voff) do { _Pragma("unroll") for (int _i = 0; _i < 2; ++_i) \
;         { unsigned vo_ = (voff) + _i * voff##_d; asm volatile("" : "+v"(vo_)); __builtin_amdgcn_global_load_lds((const unsigned*)((const char*)(gbase) + vo_), (PG8_LAS unsigned*)(lds + (bufoff) + ldsw + _i * 8192), 16, 0, 0); } } while (0)
; #define PG8_LDA(dst, b, h) do { _Pragma("unroll") for (int m = 0; m < 4; ++m) _Pragma("unroll") for (int k = 0; k < 2; ++k) dst[m][k] = *(const PG8_LAS bf16x8*)(lds + PG8_SA(b, h) + aoff + m * 2048 + k * 1024); } while (0)
; #define PG8_LDB(dst, b, h) do { _Pragma("unroll") for (int n = 0; n < 2; ++n) _Pragma("unroll") for (int k = 0; k < 2; ++k) dst[n][k] = *(const PG8_LAS bf16x8*)(lds + PG8_SB(b, h) + boff + n * 2048 + k * 1024); } while (0)
; template <class Epi, class Sched, bool ALIGN_EPI, bool F8 = false>
; __device__ __forceinline__ void gemm_phase(PG8_LAS unsigned char* lds, const Gemm g, const Sched& S, const Epi& E, const int wid) {
;     ...
;         for (int t = 0; t < nt; t += 2) {
;             const bool last = (t == nt - 2);
;             const char* a1 = cA + (size_t)(t + 1) * kstep;
;             const char* a2 = last ? nA : cA + (size_t)(t + 2) * kstep; const char* b2 = last ? nB : cB + (size_t)(t + 2) * kstep;
;             const char* a3 = a2 + kstep; const char* b3 = b2 + kstep;
;             PG8_LDB(B0, 0, 0); PG8_LDB(B1, 0, 1); PG8_SCHED; PG8_LDA(At, 0, 0); PG8_STAGE(PG8_SA(1, 1), a1 + hA, voffA);
;             PG8_WAIT_V(8); PG8_WAIT_L(0); PG8_BAR; PG8_MMA(0, 0, At, B0); PG8_MMA(0, 1, At, B1); PG8_BAR; PG8_SCHED;
;             PG8_LDA(At, 0, 1); PG8_STAGE(PG8_SB(0, 0), b2, voffB); PG8_STAGE(PG8_SB(0, 1), b2 + hB, voffB); PG8_STAGE(PG8_SA(0, 0), a2, voffA);
;             PG8_WAIT_V(8); PG8_WAIT_L(0); PG8_BAR; PG8_MMA(1, 0, At, B0); PG8_MMA(1, 1, At, B1); PG8_BAR; PG8_SCHED;
;             PG8_LDB(B0, 1, 0); PG8_LDB(B1, 1, 1); PG8_SCHED; PG8_LDA(At, 1, 0); PG8_STAGE(PG8_SA(0, 1), a2 + hA, voffA);
;             PG8_WAIT_V(8); PG8_WAIT_L(0); PG8_BAR; PG8_MMA(0, 0, At, B0); PG8_MMA(0, 1, At, B1); PG8_BAR; PG8_SCHED;
;             PG8_LDA(At, 1, 1); PG8_STAGE(PG8_SB(1, 0), b3, voffB); PG8_STAGE(PG8_SB(1, 1), b3 + hB, voffB); PG8_STAGE(PG8_SA(1, 0), a3, voffA);
;             PG8_WAIT_V(8); PG8_WAIT_L(0); PG8_BAR; PG8_MMA(1, 0, At, B0); PG8_MMA(1, 1, At, B1); PG8_BAR; PG8_SCHED;
;         }
	ds_read_b128 v[160:163], v220 offset:49152
	ds_read_b128 v[164:167], v220 offset:50176
	ds_read_b128 v[168:171], v220 offset:51200
	ds_read_b128 v[172:175], v220 offset:52224
	ds_read_b128 v[176:179], v220 offset:53248
	ds_read_b128 v[180:183], v220 offset:54272
	ds_read_b128 v[184:187], v220 offset:55296
	ds_read_b128 v[188:191], v220 offset:56320
	s_add_i32 s61, s61, s79
	s_add_u32 s100, s10, s2
	s_addc_u32 s101, s11, s3
	s_mov_b32 m0, s61
	s_nop 0
	global_load_lds_dwordx4 v217, s[100:101]
	s_add_i32 m0, s61, 0x2000
	s_add_u32 s100, s10, s2
	s_addc_u32 s101, s11, s3
	s_add_u32 s10, s10, 0x80080
	global_load_lds_dwordx4 v218, s[100:101]
	s_addc_u32 s11, s11, 0
	s_add_i32 s61, s94, s79
	s_mov_b32 m0, s61
	s_nop 0
	global_load_lds_dwordx4 v217, s[10:11]
	s_add_i32 m0, s61, 0x2000
	s_nop 0
	global_load_lds_dwordx4 v218, s[10:11]
	s_mov_b32 m0, s87
	s_add_u32 s100, s8, s2
	s_addc_u32 s101, s9, s3
	global_load_lds_dwordx4 v217, s[100:101]
	s_mov_b32 m0, s88
	s_add_u32 s100, s8, s2
	s_addc_u32 s101, s9, s3
	global_load_lds_dwordx4 v218, s[100:101]
	s_waitcnt vmcnt(8)
	s_waitcnt lgkmcnt(0)
	s_barrier
	s_setprio 1
	s_waitcnt lgkmcnt(0)
	v_mfma_f32_16x16x32_bf16 v[60:63], v[128:131], v[160:163], v[60:63]
	v_mfma_f32_16x16x32_bf16 v[56:59], v[136:139], v[160:163], v[56:59]
	v_mfma_f32_16x16x32_bf16 v[44:47], v[128:131], v[168:171], v[44:47]
	v_mfma_f32_16x16x32_bf16 v[40:43], v[136:139], v[168:171], v[40:43]
	v_mfma_f32_16x16x32_bf16 v[28:31], v[128:131], v[176:179], v[28:31]
	v_mfma_f32_16x16x32_bf16 v[24:27], v[136:139], v[176:179], v[24:27]
	v_mfma_f32_16x16x32_bf16 v[12:15], v[128:131], v[184:187], v[12:15]
	v_mfma_f32_16x16x32_bf16 v[8:11], v[136:139], v[184:187], v[8:11]
	v_mfma_f32_16x16x32_bf16 v[60:63], v[132:135], v[164:167], v[60:63]
	v_mfma_f32_16x16x32_bf16 v[56:59], v[140:143], v[164:167], v[56:59]
	v_mfma_f32_16x16x32_bf16 v[44:47], v[132:135], v[172:175], v[44:47]
	v_mfma_f32_16x16x32_bf16 v[40:43], v[140:143], v[172:175], v[40:43]
	v_mfma_f32_16x16x32_bf16 v[28:31], v[132:135], v[180:183], v[28:31]
	v_mfma_f32_16x16x32_bf16 v[24:27], v[140:143], v[180:183], v[24:27]
	v_mfma_f32_16x16x32_bf16 v[12:15], v[132:135], v[188:191], v[12:15]
	v_mfma_f32_16x16x32_bf16 v[8:11], v[140:143], v[188:191], v[8:11]
	s_setprio 0
	s_setprio 1
	v_mfma_f32_16x16x32_bf16 v[52:55], v[144:147], v[160:163], v[52:55]
	v_mfma_f32_16x16x32_bf16 v[48:51], v[152:155], v[160:163], v[48:51]
	v_mfma_f32_16x16x32_bf16 v[36:39], v[144:147], v[168:171], v[36:39]
	v_mfma_f32_16x16x32_bf16 v[32:35], v[152:155], v[168:171], v[32:35]
	v_mfma_f32_16x16x32_bf16 v[20:23], v[144:147], v[176:179], v[20:23]
	v_mfma_f32_16x16x32_bf16 v[16:19], v[152:155], v[176:179], v[16:19]
	v_mfma_f32_16x16x32_bf16 v[4:7], v[144:147], v[184:187], v[4:7]
	v_mfma_f32_16x16x32_bf16 v[0:3], v[152:155], v[184:187], v[0:3]
	v_mfma_f32_16x16x32_bf16 v[52:55], v[148:151], v[164:167], v[52:55]
	v_mfma_f32_16x16x32_bf16 v[48:51], v[156:159], v[164:167], v[48:51]
	v_mfma_f32_16x16x32_bf16 v[36:39], v[148:151], v[172:175], v[36:39]
	v_mfma_f32_16x16x32_bf16 v[32:35], v[156:159], v[172:175], v[32:35]
	v_mfma_f32_16x16x32_bf16 v[20:23], v[148:151], v[180:183], v[20:23]
	v_mfma_f32_16x16x32_bf16 v[16:19], v[156:159], v[180:183], v[16:19]
	v_mfma_f32_16x16x32_bf16 v[4:7], v[148:151], v[188:191], v[4:7]
	v_mfma_f32_16x16x32_bf16 v[0:3], v[156:159], v[188:191], v[0:3]
	s_setprio 0
	s_barrier
	s_add_u32 s6, s6, 0x100
	s_addc_u32 s7, s7, 0
	s_add_u32 s15, s15, 0x100
	s_addc_u32 s33, s33, 0
	s_cmp_ge_i32 s59, s84
	s_mov_b32 s10, s59
	s_cbranch_scc0 .LBB0_160
	s_movk_i32 s12, 0xfff
	s_movk_i32 s94, 0x90
	s_mov_b32 s71, s37
	s_and_b64 vcc, exec, s[26:27]
	s_cbranch_vccnz .LBB0_163
	s_branch .LBB0_164

; #define PG8_STAGE(bufoff, gbase, voff) do { _Pragma("unroll") for (int _i = 0; _i < 2; ++_i) \
;         { unsigned vo_ = (voff) + _i * voff##_d; asm volatile("" : "+v"(vo_)); __builtin_amdgcn_global_load_lds((const unsigned*)((const char*)(gbase) + vo_), (PG8_LAS unsigned*)(lds + (bufoff) + ldsw + _i * 8192), 16, 0, 0); } } while (0)
; #define PG8_LDA(dst, b, h) do { _Pragma("unroll") for (int m = 0; m < 4; ++m) _Pragma("unroll") for (int k = 0; k < 2; ++k) dst[m][k] = *(const PG8_LAS bf16x8*)(lds + PG8_SA(b, h) + aoff + m * 2048 + k * 1024); } while (0)
; #define PG8_LDB(dst, b, h) do { _Pragma("unroll") for (int n = 0; n < 2; ++n) _Pragma("unroll") for (int k = 0; k < 2; ++k) dst[n][k] = *(const PG8_LAS bf16x8*)(lds + PG8_SB(b, h) + boff + n * 2048 + k * 1024); } while (0)
; template <class Epi, class Sched, bool ALIGN_EPI, bool F8 = false>
; __device__ __forceinline__ void gemm_phase(PG8_LAS unsigned char* lds, const Gemm g, const Sched& S, const Epi& E, const int wid) {
;     ...
;         for (int t = 0; t < nt; t += 2) {
;             const bool last = (t == nt - 2);
;             const char* a1 = cA + (size_t)(t + 1) * kstep;
;             const char* a2 = last ? nA : cA + (size_t)(t + 2) * kstep; const char* b2 = last ? nB : cB + (size_t)(t + 2) * kstep;
;             const char* a3 = a2 + kstep; const char* b3 = b2 + kstep;
;             PG8_LDB(B0, 0, 0); PG8_LDB(B1, 0, 1); PG8_SCHED; PG8_LDA(At, 0, 0); PG8_STAGE(PG8_SA(1, 1), a1 + hA, voffA);
;             PG8_WAIT_V(8); PG8_WAIT_L(0); PG8_BAR; PG8_MMA(0, 0, At, B0); PG8_MMA(0, 1, At, B1); PG8_BAR; PG8_SCHED;
;             PG8_LDA(At, 0, 1); PG8_STAGE(PG8_SB(0, 0), b2, voffB); PG8_STAGE(PG8_SB(0, 1), b2 + hB, voffB); PG8_STAGE(PG8_SA(0, 0), a2, voffA);
;             PG8_WAIT_V(8); PG8_WAIT_L(0); PG8_BAR; PG8_MMA(1, 0, At, B0); PG8_MMA(1, 1, At, B1); PG8_BAR; PG8_SCHED;
;             PG8_LDB(B0, 1, 0); PG8_LDB(B1, 1, 1); PG8_SCHED; PG8_LDA(At, 1, 0); PG8_STAGE(PG8_SA(0, 1), a2 + hA, voffA);
;             PG8_WAIT_V(8); PG8_WAIT_L(0); PG8_BAR; PG8_MMA(0, 0, At, B0); PG8_MMA(0, 1, At, B1); PG8_BAR; PG8_SCHED;
;             PG8_LDA(At, 1, 1); PG8_STAGE(PG8_SB(1, 0), b3, voffB); PG8_STAGE(PG8_SB(1, 1), b3 + hB, voffB); PG8_STAGE(PG8_SA(1, 0), a3, voffA);
;             PG8_WAIT_V(8); PG8_WAIT_L(0); PG8_BAR; PG8_MMA(1, 0, At, B0); PG8_MMA(1, 1, At, B1); PG8_BAR; PG8_SCHED;
;         }
.LBB0_1503:
	s_add_i32 s64, s34, 2
	s_add_u32 s36, s26, 0xfffc0080
	s_addc_u32 s35, s27, -1
	s_add_i32 s65, 0, 0x10000
	s_cmp_eq_u32 s54, s34
	s_cselect_b32 s35, s25, s35
	s_cselect_b32 s34, s58, s36
	s_cselect_b32 s37, s59, s63
	s_cselect_b32 s36, s60, s61
	s_add_i32 s68, 0, 0x14000
	v_add_u32_e32 v140, s65, v148
	v_add_u32_e32 v162, s68, v148
	ds_read_b128 v[120:123], v140
	ds_read_b128 v[124:127], v140 offset:1024
	ds_read_b128 v[136:139], v140 offset:2048
	ds_read_b128 v[140:143], v140 offset:3072
	ds_read_b128 v[150:153], v162
	ds_read_b128 v[154:157], v162 offset:1024
	ds_read_b128 v[158:161], v162 offset:2048
	ds_read_b128 v[162:165], v162 offset:3072
	ds_read_b128 v[166:169], v149
	ds_read_b128 v[170:173], v149 offset:1024
	ds_read_b128 v[174:177], v149 offset:2048
	ds_read_b128 v[178:181], v149 offset:3072
	ds_read_b128 v[182:185], v149 offset:4096
	ds_read_b128 v[186:189], v149 offset:5120
	ds_read_b128 v[190:193], v149 offset:6144
	ds_read_b128 v[194:197], v149 offset:7168
	s_add_i32 m0, s45, 0xc000
	s_nop 0
	global_load_lds_dwordx4 v144, s[26:27]
	s_add_i32 m0, s45, 0xe000
	s_nop 0
	global_load_lds_dwordx4 v147, s[26:27]
	s_waitcnt vmcnt(8)
	s_waitcnt lgkmcnt(0)
	s_barrier
	s_setprio 1
	s_waitcnt lgkmcnt(0)
	v_mfma_f32_16x16x32_bf16 v[128:131], v[120:123], v[166:169], v[128:131]
	v_mfma_f32_16x16x32_bf16 v[132:135], v[136:139], v[166:169], v[132:135]
	v_mfma_f32_16x16x32_bf16 v[116:119], v[120:123], v[174:177], v[116:119]
	v_mfma_f32_16x16x32_bf16 v[112:115], v[136:139], v[174:177], v[112:115]
	v_mfma_f32_16x16x32_bf16 v[108:111], v[120:123], v[182:185], v[108:111]
	v_mfma_f32_16x16x32_bf16 v[104:107], v[136:139], v[182:185], v[104:107]
	v_mfma_f32_16x16x32_bf16 v[100:103], v[120:123], v[190:193], v[100:103]
	v_mfma_f32_16x16x32_bf16 v[96:99], v[136:139], v[190:193], v[96:99]
	v_mfma_f32_16x16x32_bf16 v[128:131], v[124:127], v[170:173], v[128:131]
	v_mfma_f32_16x16x32_bf16 v[132:135], v[140:143], v[170:173], v[132:135]
	v_mfma_f32_16x16x32_bf16 v[116:119], v[124:127], v[178:181], v[116:119]
	v_mfma_f32_16x16x32_bf16 v[112:115], v[140:143], v[178:181], v[112:115]
	v_mfma_f32_16x16x32_bf16 v[108:111], v[124:127], v[186:189], v[108:111]
	v_mfma_f32_16x16x32_bf16 v[104:107], v[140:143], v[186:189], v[104:107]
	v_mfma_f32_16x16x32_bf16 v[100:103], v[124:127], v[194:197], v[100:103]
	v_mfma_f32_16x16x32_bf16 v[96:99], v[140:143], v[194:197], v[96:99]
	s_setprio 0
	s_setprio 1
	v_mfma_f32_16x16x32_bf16 v[60:63], v[150:153], v[166:169], v[60:63]
	v_mfma_f32_16x16x32_bf16 v[56:59], v[158:161], v[166:169], v[56:59]
	v_mfma_f32_16x16x32_bf16 v[52:55], v[150:153], v[174:177], v[52:55]
	v_mfma_f32_16x16x32_bf16 v[48:51], v[158:161], v[174:177], v[48:51]
	v_mfma_f32_16x16x32_bf16 v[44:47], v[150:153], v[182:185], v[44:47]
	v_mfma_f32_16x16x32_bf16 v[40:43], v[158:161], v[182:185], v[40:43]
	v_mfma_f32_16x16x32_bf16 v[36:39], v[150:153], v[190:193], v[36:39]
	v_mfma_f32_16x16x32_bf16 v[32:35], v[158:161], v[190:193], v[32:35]
	v_mfma_f32_16x16x32_bf16 v[60:63], v[154:157], v[170:173], v[60:63]
	v_mfma_f32_16x16x32_bf16 v[56:59], v[162:165], v[170:173], v[56:59]
	v_mfma_f32_16x16x32_bf16 v[52:55], v[154:157], v[178:181], v[52:55]
	v_mfma_f32_16x16x32_bf16 v[48:51], v[162:165], v[178:181], v[48:51]
	v_mfma_f32_16x16x32_bf16 v[44:47], v[154:157], v[186:189], v[44:47]
	v_mfma_f32_16x16x32_bf16 v[40:43], v[162:165], v[186:189], v[40:43]
	v_mfma_f32_16x16x32_bf16 v[36:39], v[154:157], v[194:197], v[36:39]
	v_mfma_f32_16x16x32_bf16 v[32:35], v[162:165], v[194:197], v[32:35]
	s_setprio 0
	s_barrier
	s_add_i32 s65, s65, s44
	ds_read_b128 v[166:169], v149 offset:16384
	ds_read_b128 v[170:173], v149 offset:17408
	ds_read_b128 v[174:177], v149 offset:18432
	ds_read_b128 v[178:181], v149 offset:19456
	ds_read_b128 v[182:185], v149 offset:20480
	ds_read_b128 v[186:189], v149 offset:21504
	ds_read_b128 v[190:193], v149 offset:22528
	ds_read_b128 v[194:197], v149 offset:23552
	s_mov_b32 m0, s65
	s_nop 0
	global_load_lds_dwordx4 v145, s[36:37]
	s_add_i32 m0, s65, 0x2000
	s_add_u32 s66, s36, 0x10000
	global_load_lds_dwordx4 v146, s[36:37]
	s_addc_u32 s67, s37, 0
	s_add_i32 s65, s68, s44
	s_mov_b32 m0, s65
	s_nop 0
	global_load_lds_dwordx4 v145, s[66:67]
	s_add_i32 m0, s65, 0x2000
	s_nop 0
	global_load_lds_dwordx4 v146, s[66:67]
	s_mov_b32 m0, s45
	s_nop 0
	global_load_lds_dwordx4 v144, s[34:35]
	s_mov_b32 m0, s46
	s_nop 0
	global_load_lds_dwordx4 v147, s[34:35]
	s_waitcnt vmcnt(8)
	s_waitcnt lgkmcnt(0)
	s_barrier
	s_setprio 1
	s_waitcnt lgkmcnt(0)
	v_mfma_f32_16x16x32_bf16 v[92:95], v[120:123], v[166:169], v[92:95]
	v_mfma_f32_16x16x32_bf16 v[88:91], v[136:139], v[166:169], v[88:91]
	v_mfma_f32_16x16x32_bf16 v[84:87], v[120:123], v[174:177], v[84:87]
	v_mfma_f32_16x16x32_bf16 v[80:83], v[136:139], v[174:177], v[80:83]
	v_mfma_f32_16x16x32_bf16 v[76:79], v[120:123], v[182:185], v[76:79]
	v_mfma_f32_16x16x32_bf16 v[72:75], v[136:139], v[182:185], v[72:75]
	v_mfma_f32_16x16x32_bf16 v[68:71], v[120:123], v[190:193], v[68:71]
	v_mfma_f32_16x16x32_bf16 v[64:67], v[136:139], v[190:193], v[64:67]
	v_mfma_f32_16x16x32_bf16 v[92:95], v[124:127], v[170:173], v[92:95]
	v_mfma_f32_16x16x32_bf16 v[88:91], v[140:143], v[170:173], v[88:91]
	v_mfma_f32_16x16x32_bf16 v[84:87], v[124:127], v[178:181], v[84:87]
	v_mfma_f32_16x16x32_bf16 v[80:83], v[140:143], v[178:181], v[80:83]
	v_mfma_f32_16x16x32_bf16 v[76:79], v[124:127], v[186:189], v[76:79]
	v_mfma_f32_16x16x32_bf16 v[72:75], v[140:143], v[186:189], v[72:75]
	v_mfma_f32_16x16x32_bf16 v[68:71], v[124:127], v[194:197], v[68:71]
	v_mfma_f32_16x16x32_bf16 v[64:67], v[140:143], v[194:197], v[64:67]
	s_setprio 0
	s_setprio 1
	v_mfma_f32_16x16x32_bf16 v[28:31], v[150:153], v[166:169], v[28:31]
	v_mfma_f32_16x16x32_bf16 v[24:27], v[158:161], v[166:169], v[24:27]
	v_mfma_f32_16x16x32_bf16 v[20:23], v[150:153], v[174:177], v[20:23]
	v_mfma_f32_16x16x32_bf16 v[16:19], v[158:161], v[174:177], v[16:19]
	v_mfma_f32_16x16x32_bf16 v[12:15], v[150:153], v[182:185], v[12:15]
	v_mfma_f32_16x16x32_bf16 v[8:11], v[158:161], v[182:185], v[8:11]
	v_mfma_f32_16x16x32_bf16 v[4:7], v[150:153], v[190:193], v[4:7]
	v_mfma_f32_16x16x32_bf16 v[0:3], v[158:161], v[190:193], v[0:3]
	v_mfma_f32_16x16x32_bf16 v[28:31], v[154:157], v[170:173], v[28:31]
	v_mfma_f32_16x16x32_bf16 v[24:27], v[162:165], v[170:173], v[24:27]
	v_mfma_f32_16x16x32_bf16 v[20:23], v[154:157], v[178:181], v[20:23]
	v_mfma_f32_16x16x32_bf16 v[16:19], v[162:165], v[178:181], v[16:19]
	v_mfma_f32_16x16x32_bf16 v[12:15], v[154:157], v[186:189], v[12:15]
	v_mfma_f32_16x16x32_bf16 v[8:11], v[162:165], v[186:189], v[8:11]
	v_mfma_f32_16x16x32_bf16 v[4:7], v[154:157], v[194:197], v[4:7]
	v_mfma_f32_16x16x32_bf16 v[0:3], v[162:165], v[194:197], v[0:3]
	s_setprio 0
	s_barrier
; #define PG8_STAGE(bufoff, gbase, voff) do { _Pragma("unroll") for (int _i = 0; _i < 2; ++_i) \
;         { unsigned vo_ = (voff) + _i * voff##_d; asm volatile("" : "+v"(vo_)); __builtin_amdgcn_global_load_lds((const unsigned*)((const char*)(gbase) + vo_), (PG8_LAS unsigned*)(lds + (bufoff) + ldsw + _i * 8192), 16, 0, 0); } } while (0)
; #define PG8_LDA(dst, b, h) do { _Pragma("unroll") for (int m = 0; m < 4; ++m) _Pragma("unroll") for (int k = 0; k < 2; ++k) dst[m][k] = *(const PG8_LAS bf16x8*)(lds + PG8_SA(b, h) + aoff + m * 2048 + k * 1024); } while (0)
; #define PG8_LDB(dst, b, h) do { _Pragma("unroll") for (int n = 0; n < 2; ++n) _Pragma("unroll") for (int k = 0; k < 2; ++k) dst[n][k] = *(const PG8_LAS bf16x8*)(lds + PG8_SB(b, h) + boff + n * 2048 + k * 1024); } while (0)
; template <class Epi, class Sched, bool ALIGN_EPI, bool F8 = false>
; __device__ __forceinline__ void gemm_phase(PG8_LAS unsigned char* lds, const Gemm g, const Sched& S, const Epi& E, const int wid) {
;     ...
;         for (int t = 0; t < nt; t += 2) {
;             const bool last = (t == nt - 2);
;             const char* a1 = cA + (size_t)(t + 1) * kstep;
;             const char* a2 = last ? nA : cA + (size_t)(t + 2) * kstep; const char* b2 = last ? nB : cB + (size_t)(t + 2) * kstep;
;             const char* a3 = a2 + kstep; const char* b3 = b2 + kstep;
;             PG8_LDB(B0, 0, 0); PG8_LDB(B1, 0, 1); PG8_SCHED; PG8_LDA(At, 0, 0); PG8_STAGE(PG8_SA(1, 1), a1 + hA, voffA);
;             PG8_WAIT_V(8); PG8_WAIT_L(0); PG8_BAR; PG8_MMA(0, 0, At, B0); PG8_MMA(0, 1, At, B1); PG8_BAR; PG8_SCHED;
;             PG8_LDA(At, 0, 1); PG8_STAGE(PG8_SB(0, 0), b2, voffB); PG8_STAGE(PG8_SB(0, 1), b2 + hB, voffB); PG8_STAGE(PG8_SA(0, 0), a2, voffA);
;             PG8_WAIT_V(8); PG8_WAIT_L(0); PG8_BAR; PG8_MMA(1, 0, At, B0); PG8_MMA(1, 1, At, B1); PG8_BAR; PG8_SCHED;
;             PG8_LDB(B0, 1, 0); PG8_LDB(B1, 1, 1); PG8_SCHED; PG8_LDA(At, 1, 0); PG8_STAGE(PG8_SA(0, 1), a2 + hA, voffA);
;             PG8_WAIT_V(8); PG8_WAIT_L(0); PG8_BAR; PG8_MMA(0, 0, At, B0); PG8_MMA(0, 1, At, B1); PG8_BAR; PG8_SCHED;
;             PG8_LDA(At, 1, 1); PG8_STAGE(PG8_SB(1, 0), b3, voffB); PG8_STAGE(PG8_SB(1, 1), b3 + hB, voffB); PG8_STAGE(PG8_SA(1, 0), a3, voffA);
;             PG8_WAIT_V(8); PG8_WAIT_L(0); PG8_BAR; PG8_MMA(1, 0, At, B0); PG8_MMA(1, 1, At, B1); PG8_BAR; PG8_SCHED;
;         }
	s_add_i32 s65, 0, 0x18000
	s_add_i32 s68, 0, 0x1c000
	v_add_u32_e32 v140, s65, v148
	v_add_u32_e32 v162, s68, v148
	ds_read_b128 v[120:123], v140
	ds_read_b128 v[124:127], v140 offset:1024
	ds_read_b128 v[136:139], v140 offset:2048
	ds_read_b128 v[140:143], v140 offset:3072
	ds_read_b128 v[150:153], v162
	ds_read_b128 v[154:157], v162 offset:1024
	ds_read_b128 v[158:161], v162 offset:2048
	ds_read_b128 v[162:165], v162 offset:3072
	s_add_u32 s66, s34, 0x40000
	s_mov_b32 m0, s47
	ds_read_b128 v[166:169], v149 offset:32768
	ds_read_b128 v[170:173], v149 offset:33792
	ds_read_b128 v[174:177], v149 offset:34816
	ds_read_b128 v[178:181], v149 offset:35840
	ds_read_b128 v[182:185], v149 offset:36864
	ds_read_b128 v[186:189], v149 offset:37888
	ds_read_b128 v[190:193], v149 offset:38912
	ds_read_b128 v[194:197], v149 offset:39936
	s_addc_u32 s67, s35, 0
	s_nop 0
	global_load_lds_dwordx4 v144, s[66:67]
	s_mov_b32 m0, s48
	s_nop 0
	global_load_lds_dwordx4 v147, s[66:67]
	s_waitcnt vmcnt(8)
	s_waitcnt lgkmcnt(0)
	s_barrier
	s_setprio 1
	s_waitcnt lgkmcnt(0)
	v_mfma_f32_16x16x32_bf16 v[128:131], v[120:123], v[166:169], v[128:131]
	v_mfma_f32_16x16x32_bf16 v[132:135], v[136:139], v[166:169], v[132:135]
	v_mfma_f32_16x16x32_bf16 v[116:119], v[120:123], v[174:177], v[116:119]
	v_mfma_f32_16x16x32_bf16 v[112:115], v[136:139], v[174:177], v[112:115]
	v_mfma_f32_16x16x32_bf16 v[108:111], v[120:123], v[182:185], v[108:111]
	v_mfma_f32_16x16x32_bf16 v[104:107], v[136:139], v[182:185], v[104:107]
	v_mfma_f32_16x16x32_bf16 v[100:103], v[120:123], v[190:193], v[100:103]
	v_mfma_f32_16x16x32_bf16 v[96:99], v[136:139], v[190:193], v[96:99]
	v_mfma_f32_16x16x32_bf16 v[128:131], v[124:127], v[170:173], v[128:131]
	v_mfma_f32_16x16x32_bf16 v[132:135], v[140:143], v[170:173], v[132:135]
	v_mfma_f32_16x16x32_bf16 v[116:119], v[124:127], v[178:181], v[116:119]
	v_mfma_f32_16x16x32_bf16 v[112:115], v[140:143], v[178:181], v[112:115]
	v_mfma_f32_16x16x32_bf16 v[108:111], v[124:127], v[186:189], v[108:111]
	v_mfma_f32_16x16x32_bf16 v[104:107], v[140:143], v[186:189], v[104:107]
	v_mfma_f32_16x16x32_bf16 v[100:103], v[124:127], v[194:197], v[100:103]
	v_mfma_f32_16x16x32_bf16 v[96:99], v[140:143], v[194:197], v[96:99]
	s_setprio 0
	s_setprio 1
	v_mfma_f32_16x16x32_bf16 v[60:63], v[150:153], v[166:169], v[60:63]
	v_mfma_f32_16x16x32_bf16 v[56:59], v[158:161], v[166:169], v[56:59]
	v_mfma_f32_16x16x32_bf16 v[52:55], v[150:153], v[174:177], v[52:55]
	v_mfma_f32_16x16x32_bf16 v[48:51], v[158:161], v[174:177], v[48:51]
	v_mfma_f32_16x16x32_bf16 v[44:47], v[150:153], v[182:185], v[44:47]
	v_mfma_f32_16x16x32_bf16 v[40:43], v[158:161], v[182:185], v[40:43]
	v_mfma_f32_16x16x32_bf16 v[36:39], v[150:153], v[190:193], v[36:39]
	v_mfma_f32_16x16x32_bf16 v[32:35], v[158:161], v[190:193], v[32:35]
	v_mfma_f32_16x16x32_bf16 v[60:63], v[154:157], v[170:173], v[60:63]
	v_mfma_f32_16x16x32_bf16 v[56:59], v[162:165], v[170:173], v[56:59]
	v_mfma_f32_16x16x32_bf16 v[52:55], v[154:157], v[178:181], v[52:55]
	v_mfma_f32_16x16x32_bf16 v[48:51], v[162:165], v[178:181], v[48:51]
	v_mfma_f32_16x16x32_bf16 v[44:47], v[154:157], v[186:189], v[44:47]
	v_mfma_f32_16x16x32_bf16 v[40:43], v[162:165], v[186:189], v[40:43]
	v_mfma_f32_16x16x32_bf16 v[36:39], v[154:157], v[194:197], v[36:39]
	v_mfma_f32_16x16x32_bf16 v[32:35], v[162:165], v[194:197], v[32:35]
	s_setprio 0
	s_barrier
	ds_read_b128 v[166:169], v149 offset:49152
	ds_read_b128 v[170:173], v149 offset:50176
	ds_read_b128 v[174:177], v149 offset:51200
	ds_read_b128 v[178:181], v149 offset:52224
	ds_read_b128 v[182:185], v149 offset:53248
	ds_read_b128 v[186:189], v149 offset:54272
	ds_read_b128 v[190:193], v149 offset:55296
	ds_read_b128 v[194:197], v149 offset:56320
	s_add_i32 s65, s65, s44
	s_add_u32 s100, s36, s2
	s_addc_u32 s101, s37, s3
	s_mov_b32 m0, s65
	s_nop 0
	global_load_lds_dwordx4 v145, s[100:101]
	s_add_i32 m0, s65, 0x2000
	s_add_u32 s100, s36, s2
	s_addc_u32 s101, s37, s3
	s_add_u32 s36, s36, 0x10080
	s_addc_u32 s37, s37, 0
	s_add_i32 s65, s68, s44
	global_load_lds_dwordx4 v146, s[100:101]
	s_mov_b32 m0, s65
	s_nop 0
	global_load_lds_dwordx4 v145, s[36:37]
	s_add_i32 m0, s65, 0x2000
	s_nop 0
	global_load_lds_dwordx4 v146, s[36:37]
	s_mov_b32 m0, s51
	s_add_u32 s100, s34, s2
	s_addc_u32 s101, s35, s3
	global_load_lds_dwordx4 v144, s[100:101]
	s_mov_b32 m0, s52
	s_add_u32 s100, s34, s2
	s_addc_u32 s101, s35, s3
	global_load_lds_dwordx4 v147, s[100:101]
	s_waitcnt vmcnt(8)
	s_waitcnt lgkmcnt(0)
	s_barrier
	s_setprio 1
	s_waitcnt lgkmcnt(0)
	v_mfma_f32_16x16x32_bf16 v[92:95], v[120:123], v[166:169], v[92:95]
	v_mfma_f32_16x16x32_bf16 v[88:91], v[136:139], v[166:169], v[88:91]
	v_mfma_f32_16x16x32_bf16 v[84:87], v[120:123], v[174:177], v[84:87]
	v_mfma_f32_16x16x32_bf16 v[80:83], v[136:139], v[174:177], v[80:83]
	v_mfma_f32_16x16x32_bf16 v[76:79], v[120:123], v[182:185], v[76:79]
	v_mfma_f32_16x16x32_bf16 v[72:75], v[136:139], v[182:185], v[72:75]
	v_mfma_f32_16x16x32_bf16 v[68:71], v[120:123], v[190:193], v[68:71]
	v_mfma_f32_16x16x32_bf16 v[64:67], v[136:139], v[190:193], v[64:67]
	v_mfma_f32_16x16x32_bf16 v[92:95], v[124:127], v[170:173], v[92:95]
	v_mfma_f32_16x16x32_bf16 v[88:91], v[140:143], v[170:173], v[88:91]
	v_mfma_f32_16x16x32_bf16 v[84:87], v[124:127], v[178:181], v[84:87]
	v_mfma_f32_16x16x32_bf16 v[80:83], v[140:143], v[178:181], v[80:83]
	v_mfma_f32_16x16x32_bf16 v[76:79], v[124:127], v[186:189], v[76:79]
	v_mfma_f32_16x16x32_bf16 v[72:75], v[140:143], v[186:189], v[72:75]
	v_mfma_f32_16x16x32_bf16 v[68:71], v[124:127], v[194:197], v[68:71]
	v_mfma_f32_16x16x32_bf16 v[64:67], v[140:143], v[194:197], v[64:67]
	s_setprio 0
	s_setprio 1
	v_mfma_f32_16x16x32_bf16 v[28:31], v[150:153], v[166:169], v[28:31]
	v_mfma_f32_16x16x32_bf16 v[24:27], v[158:161], v[166:169], v[24:27]
	v_mfma_f32_16x16x32_bf16 v[20:23], v[150:153], v[174:177], v[20:23]
	v_mfma_f32_16x16x32_bf16 v[16:19], v[158:161], v[174:177], v[16:19]
	v_mfma_f32_16x16x32_bf16 v[12:15], v[150:153], v[182:185], v[12:15]
	v_mfma_f32_16x16x32_bf16 v[8:11], v[158:161], v[182:185], v[8:11]
	v_mfma_f32_16x16x32_bf16 v[4:7], v[150:153], v[190:193], v[4:7]
	v_mfma_f32_16x16x32_bf16 v[0:3], v[158:161], v[190:193], v[0:3]
	v_mfma_f32_16x16x32_bf16 v[28:31], v[154:157], v[170:173], v[28:31]
	v_mfma_f32_16x16x32_bf16 v[24:27], v[162:165], v[170:173], v[24:27]
	v_mfma_f32_16x16x32_bf16 v[20:23], v[154:157], v[178:181], v[20:23]
	v_mfma_f32_16x16x32_bf16 v[16:19], v[162:165], v[178:181], v[16:19]
	v_mfma_f32_16x16x32_bf16 v[12:15], v[154:157], v[186:189], v[12:15]
	v_mfma_f32_16x16x32_bf16 v[8:11], v[162:165], v[186:189], v[8:11]
	v_mfma_f32_16x16x32_bf16 v[4:7], v[154:157], v[194:197], v[4:7]
	v_mfma_f32_16x16x32_bf16 v[0:3], v[162:165], v[194:197], v[0:3]
	s_setprio 0
	s_barrier
	s_add_u32 s26, s26, 0x100
	s_addc_u32 s27, s27, 0
	s_add_u32 s61, s61, 0x100
	s_addc_u32 s63, s63, 0
	s_cmp_ge_i32 s64, s53
	s_mov_b32 s34, s64
	s_cbranch_scc0 .LBB0_1503

; #define PG8_STAGE(bufoff, gbase, voff) do { _Pragma("unroll") for (int _i = 0; _i < 2; ++_i) \
;         { unsigned vo_ = (voff) + _i * voff##_d; asm volatile("" : "+v"(vo_)); __builtin_amdgcn_global_load_lds((const unsigned*)((const char*)(gbase) + vo_), (PG8_LAS unsigned*)(lds + (bufoff) + ldsw + _i * 8192), 16, 0, 0); } } while (0)
; #define PG8_LDA(dst, b, h) do { _Pragma("unroll") for (int m = 0; m < 4; ++m) _Pragma("unroll") for (int k = 0; k < 2; ++k) dst[m][k] = *(const PG8_LAS bf16x8*)(lds + PG8_SA(b, h) + aoff + m * 2048 + k * 1024); } while (0)
; #define PG8_LDB(dst, b, h) do { _Pragma("unroll") for (int n = 0; n < 2; ++n) _Pragma("unroll") for (int k = 0; k < 2; ++k) dst[n][k] = *(const PG8_LAS bf16x8*)(lds + PG8_SB(b, h) + boff + n * 2048 + k * 1024); } while (0)
; template <class Epi, class Sched, bool ALIGN_EPI, bool F8 = false>
; __device__ __forceinline__ void gemm_phase(PG8_LAS unsigned char* lds, const Gemm g, const Sched& S, const Epi& E, const int wid) {
;     ...
;         for (int t = 0; t < nt; t += 2) {
;             const bool last = (t == nt - 2);
;             const char* a1 = cA + (size_t)(t + 1) * kstep;
;             const char* a2 = last ? nA : cA + (size_t)(t + 2) * kstep; const char* b2 = last ? nB : cB + (size_t)(t + 2) * kstep;
;             const char* a3 = a2 + kstep; const char* b3 = b2 + kstep;
;             PG8_LDB(B0, 0, 0); PG8_LDB(B1, 0, 1); PG8_SCHED; PG8_LDA(At, 0, 0); PG8_STAGE(PG8_SA(1, 1), a1 + hA, voffA);
;             PG8_WAIT_V(8); PG8_WAIT_L(0); PG8_BAR; PG8_MMA(0, 0, At, B0); PG8_MMA(0, 1, At, B1); PG8_BAR; PG8_SCHED;
;             PG8_LDA(At, 0, 1); PG8_STAGE(PG8_SB(0, 0), b2, voffB); PG8_STAGE(PG8_SB(0, 1), b2 + hB, voffB); PG8_STAGE(PG8_SA(0, 0), a2, voffA);
;             PG8_WAIT_V(8); PG8_WAIT_L(0); PG8_BAR; PG8_MMA(1, 0, At, B0); PG8_MMA(1, 1, At, B1); PG8_BAR; PG8_SCHED;
;             PG8_LDB(B0, 1, 0); PG8_LDB(B1, 1, 1); PG8_SCHED; PG8_LDA(At, 1, 0); PG8_STAGE(PG8_SA(0, 1), a2 + hA, voffA);
;             PG8_WAIT_V(8); PG8_WAIT_L(0); PG8_BAR; PG8_MMA(0, 0, At, B0); PG8_MMA(0, 1, At, B1); PG8_BAR; PG8_SCHED;
;             PG8_LDA(At, 1, 1); PG8_STAGE(PG8_SB(1, 0), b3, voffB); PG8_STAGE(PG8_SB(1, 1), b3 + hB, voffB); PG8_STAGE(PG8_SA(1, 0), a3, voffA);
;             PG8_WAIT_V(8); PG8_WAIT_L(0); PG8_BAR; PG8_MMA(1, 0, At, B0); PG8_MMA(1, 1, At, B1); PG8_BAR; PG8_SCHED;
;         }
.LBB0_1770:
	s_add_i32 s59, s28, 2
	s_add_u32 s30, s26, 0xfffe0080
	s_addc_u32 s29, s27, -1
	s_add_i32 s60, 0, 0x10000
	s_cmp_eq_u32 s51, s28
	s_cselect_b32 s29, s13, s29
	s_cselect_b32 s28, s15, s30
	s_cselect_b32 s31, s55, s58
	s_cselect_b32 s30, s56, s57
	s_add_i32 s62, 0, 0x14000
	v_add_u32_e32 v140, s60, v186
	v_add_u32_e32 v156, s62, v186
	ds_read_b128 v[128:131], v140
	ds_read_b128 v[132:135], v140 offset:1024
	ds_read_b128 v[136:139], v140 offset:2048
	ds_read_b128 v[140:143], v140 offset:3072
	ds_read_b128 v[144:147], v156
	ds_read_b128 v[148:151], v156 offset:1024
	ds_read_b128 v[152:155], v156 offset:2048
	ds_read_b128 v[156:159], v156 offset:3072
	ds_read_b128 v[160:163], v187
	ds_read_b128 v[164:167], v187 offset:1024
	ds_read_b128 v[168:171], v187 offset:2048
	ds_read_b128 v[172:175], v187 offset:3072
	ds_read_b128 v[188:191], v187 offset:4096
	ds_read_b128 v[192:195], v187 offset:5120
	ds_read_b128 v[206:209], v187 offset:6144
	ds_read_b128 v[210:213], v187 offset:7168
	s_add_i32 m0, s40, 0xc000
	s_nop 0
	global_load_lds_dwordx4 v182, s[26:27]
	s_add_i32 m0, s40, 0xe000
	s_nop 0
	global_load_lds_dwordx4 v185, s[26:27]
	s_waitcnt vmcnt(8)
	s_waitcnt lgkmcnt(0)
	s_barrier
	s_setprio 1
	s_waitcnt lgkmcnt(0)
	v_mfma_f32_16x16x128_f8f6f4 v[124:127], v[128:135], v[160:167], v[124:127]
	v_mfma_f32_16x16x128_f8f6f4 v[120:123], v[136:143], v[160:167], v[120:123]
	v_mfma_f32_16x16x128_f8f6f4 v[116:119], v[128:135], v[168:175], v[116:119]
	v_mfma_f32_16x16x128_f8f6f4 v[112:115], v[136:143], v[168:175], v[112:115]
	v_mfma_f32_16x16x128_f8f6f4 v[104:107], v[128:135], v[188:195], v[104:107]
	v_mfma_f32_16x16x128_f8f6f4 v[176:179], v[136:143], v[188:195], v[96:99]
	v_mfma_f32_16x16x128_f8f6f4 v[196:199], v[128:135], v[206:213], v[88:91]
	v_mfma_f32_16x16x128_f8f6f4 v[202:205], v[136:143], v[206:213], v[80:83]
	s_setprio 0
	s_setprio 1
	v_mfma_f32_16x16x128_f8f6f4 v[108:111], v[144:151], v[160:167], v[108:111]
	v_mfma_f32_16x16x128_f8f6f4 v[100:103], v[152:159], v[160:167], v[100:103]
	v_mfma_f32_16x16x128_f8f6f4 v[60:63], v[152:159], v[206:213], v[60:63]
	v_mfma_f32_16x16x128_f8f6f4 v[160:163], v[144:151], v[168:175], v[92:95]
	v_mfma_f32_16x16x128_f8f6f4 v[164:167], v[152:159], v[168:175], v[84:87]
	v_mfma_f32_16x16x128_f8f6f4 v[168:171], v[144:151], v[188:195], v[76:79]
	v_mfma_f32_16x16x128_f8f6f4 v[172:175], v[152:159], v[188:195], v[72:75]
	v_mfma_f32_16x16x128_f8f6f4 v[188:191], v[144:151], v[206:213], v[68:71]
	s_setprio 0
	s_barrier
	s_add_i32 s60, s60, s39
	s_nop 2
	ds_read_b128 v[68:71], v187 offset:16384
	ds_read_b128 v[72:75], v187 offset:17408
	ds_read_b128 v[76:79], v187 offset:18432
	ds_read_b128 v[80:83], v187 offset:19456
	ds_read_b128 v[84:87], v187 offset:20480
	ds_read_b128 v[88:91], v187 offset:21504
	ds_read_b128 v[92:95], v187 offset:22528
	ds_read_b128 v[96:99], v187 offset:23552
	s_mov_b32 m0, s60
	s_nop 0
	global_load_lds_dwordx4 v183, s[30:31]
	s_add_i32 m0, s60, 0x2000
	s_add_u32 s60, s30, 0x20000
	global_load_lds_dwordx4 v184, s[30:31]
	s_addc_u32 s61, s31, 0
	s_add_i32 s62, s62, s39
	s_mov_b32 m0, s62
	s_nop 0
	global_load_lds_dwordx4 v183, s[60:61]
	s_add_i32 m0, s62, 0x2000
	s_nop 0
	global_load_lds_dwordx4 v184, s[60:61]
	s_mov_b32 m0, s40
	s_nop 0
	global_load_lds_dwordx4 v182, s[28:29]
	s_mov_b32 m0, s41
	s_nop 0
	global_load_lds_dwordx4 v185, s[28:29]
	s_waitcnt vmcnt(8)
	s_waitcnt lgkmcnt(0)
	s_barrier
	s_setprio 1
	s_waitcnt lgkmcnt(0)
	v_mfma_f32_16x16x128_f8f6f4 v[64:67], v[128:135], v[68:75], v[64:67]
	v_mfma_f32_16x16x128_f8f6f4 v[56:59], v[136:143], v[68:75], v[56:59]
	v_mfma_f32_16x16x128_f8f6f4 v[52:55], v[128:135], v[76:83], v[52:55]
	v_mfma_f32_16x16x128_f8f6f4 v[48:51], v[136:143], v[76:83], v[48:51]
	v_mfma_f32_16x16x128_f8f6f4 v[192:195], v[128:135], v[84:91], v[40:43]
	v_mfma_f32_16x16x128_f8f6f4 v[206:209], v[136:143], v[84:91], v[32:35]
	v_mfma_f32_16x16x128_f8f6f4 v[210:213], v[128:135], v[92:99], v[24:27]
	v_mfma_f32_16x16x128_f8f6f4 v[214:217], v[136:143], v[92:99], v[16:19]
	s_setprio 0
	s_setprio 1
	v_mfma_f32_16x16x128_f8f6f4 v[218:221], v[144:151], v[68:75], v[44:47]
	v_mfma_f32_16x16x128_f8f6f4 v[224:227], v[152:159], v[68:75], v[36:39]
	v_mfma_f32_16x16x128_f8f6f4 v[228:231], v[144:151], v[76:83], v[28:31]
	v_mfma_f32_16x16x128_f8f6f4 v[232:235], v[152:159], v[76:83], v[20:23]
	v_mfma_f32_16x16x128_f8f6f4 v[236:239], v[144:151], v[84:91], v[12:15]
	v_mfma_f32_16x16x128_f8f6f4 v[242:245], v[152:159], v[84:91], v[8:11]
	v_mfma_f32_16x16x128_f8f6f4 v[246:249], v[144:151], v[92:99], v[4:7]
	v_mfma_f32_16x16x128_f8f6f4 v[250:253], v[152:159], v[92:99], v[0:3]
	s_setprio 0
	s_barrier
	s_add_i32 s62, 0, 0x18000
	s_add_i32 s63, 0, 0x1c000
	v_add_u32_e32 v12, s62, v186
	v_add_u32_e32 v16, s63, v186
	s_nop 0
	ds_read_b128 v[0:3], v12
	ds_read_b128 v[4:7], v12 offset:1024
	ds_read_b128 v[8:11], v12 offset:2048
	ds_read_b128 v[12:15], v12 offset:3072
	ds_read_b128 v[128:131], v16
	ds_read_b128 v[132:135], v16 offset:1024
	ds_read_b128 v[136:139], v16 offset:2048
	ds_read_b128 v[140:143], v16 offset:3072
	s_add_u32 s60, s28, 0x20000
	s_mov_b32 m0, s42
	ds_read_b128 v[16:19], v187 offset:32768
	ds_read_b128 v[20:23], v187 offset:33792
	ds_read_b128 v[24:27], v187 offset:34816
	ds_read_b128 v[28:31], v187 offset:35840
	ds_read_b128 v[32:35], v187 offset:36864
	ds_read_b128 v[36:39], v187 offset:37888
	ds_read_b128 v[40:43], v187 offset:38912
	ds_read_b128 v[44:47], v187 offset:39936
	s_addc_u32 s61, s29, 0
	s_nop 0
	global_load_lds_dwordx4 v182, s[60:61]
	s_mov_b32 m0, s43
	s_nop 0
	global_load_lds_dwordx4 v185, s[60:61]
	s_waitcnt vmcnt(8)
	s_waitcnt lgkmcnt(0)
	s_barrier
; #define PG8_STAGE(bufoff, gbase, voff) do { _Pragma("unroll") for (int _i = 0; _i < 2; ++_i) \
;         { unsigned vo_ = (voff) + _i * voff##_d; asm volatile("" : "+v"(vo_)); __builtin_amdgcn_global_load_lds((const unsigned*)((const char*)(gbase) + vo_), (PG8_LAS unsigned*)(lds + (bufoff) + ldsw + _i * 8192), 16, 0, 0); } } while (0)
; #define PG8_LDA(dst, b, h) do { _Pragma("unroll") for (int m = 0; m < 4; ++m) _Pragma("unroll") for (int k = 0; k < 2; ++k) dst[m][k] = *(const PG8_LAS bf16x8*)(lds + PG8_SA(b, h) + aoff + m * 2048 + k * 1024); } while (0)
; #define PG8_LDB(dst, b, h) do { _Pragma("unroll") for (int n = 0; n < 2; ++n) _Pragma("unroll") for (int k = 0; k < 2; ++k) dst[n][k] = *(const PG8_LAS bf16x8*)(lds + PG8_SB(b, h) + boff + n * 2048 + k * 1024); } while (0)
; template <class Epi, class Sched, bool ALIGN_EPI, bool F8 = false>
; __device__ __forceinline__ void gemm_phase(PG8_LAS unsigned char* lds, const Gemm g, const Sched& S, const Epi& E, const int wid) {
;     ...
;         for (int t = 0; t < nt; t += 2) {
;             const bool last = (t == nt - 2);
;             const char* a1 = cA + (size_t)(t + 1) * kstep;
;             const char* a2 = last ? nA : cA + (size_t)(t + 2) * kstep; const char* b2 = last ? nB : cB + (size_t)(t + 2) * kstep;
;             const char* a3 = a2 + kstep; const char* b3 = b2 + kstep;
;             PG8_LDB(B0, 0, 0); PG8_LDB(B1, 0, 1); PG8_SCHED; PG8_LDA(At, 0, 0); PG8_STAGE(PG8_SA(1, 1), a1 + hA, voffA);
;             PG8_WAIT_V(8); PG8_WAIT_L(0); PG8_BAR; PG8_MMA(0, 0, At, B0); PG8_MMA(0, 1, At, B1); PG8_BAR; PG8_SCHED;
;             PG8_LDA(At, 0, 1); PG8_STAGE(PG8_SB(0, 0), b2, voffB); PG8_STAGE(PG8_SB(0, 1), b2 + hB, voffB); PG8_STAGE(PG8_SA(0, 0), a2, voffA);
;             PG8_WAIT_V(8); PG8_WAIT_L(0); PG8_BAR; PG8_MMA(1, 0, At, B0); PG8_MMA(1, 1, At, B1); PG8_BAR; PG8_SCHED;
;             PG8_LDB(B0, 1, 0); PG8_LDB(B1, 1, 1); PG8_SCHED; PG8_LDA(At, 1, 0); PG8_STAGE(PG8_SA(0, 1), a2 + hA, voffA);
;             PG8_WAIT_V(8); PG8_WAIT_L(0); PG8_BAR; PG8_MMA(0, 0, At, B0); PG8_MMA(0, 1, At, B1); PG8_BAR; PG8_SCHED;
;             PG8_LDA(At, 1, 1); PG8_STAGE(PG8_SB(1, 0), b3, voffB); PG8_STAGE(PG8_SB(1, 1), b3 + hB, voffB); PG8_STAGE(PG8_SA(1, 0), a3, voffA);
;             PG8_WAIT_V(8); PG8_WAIT_L(0); PG8_BAR; PG8_MMA(1, 0, At, B0); PG8_MMA(1, 1, At, B1); PG8_BAR; PG8_SCHED;
;         }
	s_setprio 1
	s_waitcnt lgkmcnt(0)
	v_mfma_f32_16x16x128_f8f6f4 v[124:127], v[0:7], v[16:23], v[124:127]
	v_mfma_f32_16x16x128_f8f6f4 v[120:123], v[8:15], v[16:23], v[120:123]
	v_mfma_f32_16x16x128_f8f6f4 v[116:119], v[0:7], v[24:31], v[116:119]
	v_mfma_f32_16x16x128_f8f6f4 v[112:115], v[8:15], v[24:31], v[112:115]
	v_mfma_f32_16x16x128_f8f6f4 v[104:107], v[0:7], v[32:39], v[104:107]
	v_mfma_f32_16x16x128_f8f6f4 v[96:99], v[8:15], v[32:39], v[176:179]
	v_mfma_f32_16x16x128_f8f6f4 v[88:91], v[0:7], v[40:47], v[196:199]
	v_mfma_f32_16x16x128_f8f6f4 v[80:83], v[8:15], v[40:47], v[202:205]
	s_setprio 0
	s_setprio 1
	v_mfma_f32_16x16x128_f8f6f4 v[108:111], v[128:135], v[16:23], v[108:111]
	v_mfma_f32_16x16x128_f8f6f4 v[100:103], v[136:143], v[16:23], v[100:103]
	v_mfma_f32_16x16x128_f8f6f4 v[92:95], v[128:135], v[24:31], v[160:163]
	v_mfma_f32_16x16x128_f8f6f4 v[84:87], v[136:143], v[24:31], v[164:167]
	v_mfma_f32_16x16x128_f8f6f4 v[76:79], v[128:135], v[32:39], v[168:171]
	v_mfma_f32_16x16x128_f8f6f4 v[72:75], v[136:143], v[32:39], v[172:175]
	v_mfma_f32_16x16x128_f8f6f4 v[68:71], v[128:135], v[40:47], v[188:191]
	v_mfma_f32_16x16x128_f8f6f4 v[60:63], v[136:143], v[40:47], v[60:63]
	s_setprio 0
	s_barrier
	ds_read_b128 v[144:147], v187 offset:49152
	ds_read_b128 v[148:151], v187 offset:50176
	ds_read_b128 v[152:155], v187 offset:51200
	ds_read_b128 v[156:159], v187 offset:52224
	ds_read_b128 v[160:163], v187 offset:53248
	ds_read_b128 v[164:167], v187 offset:54272
	ds_read_b128 v[168:171], v187 offset:55296
	ds_read_b128 v[172:175], v187 offset:56320
	s_add_i32 s60, s62, s39
	s_add_u32 s100, s30, s2
	s_addc_u32 s101, s31, s3
	s_mov_b32 m0, s60
	s_nop 0
	global_load_lds_dwordx4 v183, s[100:101]
	s_add_i32 m0, s60, 0x2000
	s_add_u32 s100, s30, s2
	s_addc_u32 s101, s31, s3
	s_add_u32 s30, s30, 0x20080
	global_load_lds_dwordx4 v184, s[100:101]
	s_addc_u32 s31, s31, 0
	s_add_i32 s60, s63, s39
	s_mov_b32 m0, s60
	s_nop 0
	global_load_lds_dwordx4 v183, s[30:31]
	s_add_i32 m0, s60, 0x2000
	s_nop 0
	global_load_lds_dwordx4 v184, s[30:31]
	s_mov_b32 m0, s49
	s_add_u32 s100, s28, s2
	s_addc_u32 s101, s29, s3
	global_load_lds_dwordx4 v182, s[100:101]
	s_mov_b32 m0, s50
	s_add_u32 s100, s28, s2
	s_addc_u32 s101, s29, s3
	global_load_lds_dwordx4 v185, s[100:101]
	s_waitcnt vmcnt(8)
	s_waitcnt lgkmcnt(0)
	s_barrier
	s_setprio 1
	s_waitcnt lgkmcnt(0)
	v_mfma_f32_16x16x128_f8f6f4 v[64:67], v[0:7], v[144:151], v[64:67]
	v_mfma_f32_16x16x128_f8f6f4 v[56:59], v[8:15], v[144:151], v[56:59]
	v_mfma_f32_16x16x128_f8f6f4 v[52:55], v[0:7], v[152:159], v[52:55]
	v_mfma_f32_16x16x128_f8f6f4 v[48:51], v[8:15], v[152:159], v[48:51]
	v_mfma_f32_16x16x128_f8f6f4 v[40:43], v[0:7], v[160:167], v[192:195]
	v_mfma_f32_16x16x128_f8f6f4 v[32:35], v[8:15], v[160:167], v[206:209]
	v_mfma_f32_16x16x128_f8f6f4 v[24:27], v[0:7], v[168:175], v[210:213]
	v_mfma_f32_16x16x128_f8f6f4 v[16:19], v[8:15], v[168:175], v[214:217]
	s_setprio 0
	s_setprio 1
	v_mfma_f32_16x16x128_f8f6f4 v[44:47], v[128:135], v[144:151], v[218:221]
	v_mfma_f32_16x16x128_f8f6f4 v[36:39], v[136:143], v[144:151], v[224:227]
	v_mfma_f32_16x16x128_f8f6f4 v[28:31], v[128:135], v[152:159], v[228:231]
	v_mfma_f32_16x16x128_f8f6f4 v[20:23], v[136:143], v[152:159], v[232:235]
	v_mfma_f32_16x16x128_f8f6f4 v[12:15], v[128:135], v[160:167], v[236:239]
	v_mfma_f32_16x16x128_f8f6f4 v[8:11], v[136:143], v[160:167], v[242:245]
	v_mfma_f32_16x16x128_f8f6f4 v[4:7], v[128:135], v[168:175], v[246:249]
	v_mfma_f32_16x16x128_f8f6f4 v[0:3], v[136:143], v[168:175], v[250:253]
	s_setprio 0
	s_barrier
	s_add_u32 s26, s26, 0x100
	s_addc_u32 s27, s27, 0
	s_add_u32 s57, s57, 0x100
	s_addc_u32 s58, s58, 0
	s_cmp_ge_i32 s59, s46
	s_mov_b32 s28, s59
	s_cbranch_scc0 .LBB0_1770
; __device__ __forceinline__ unsigned pk2(float lo, float hi) { typedef float f2_ __attribute__((ext_vector_type(2))); const bf16x2n_t b = __builtin_convertvector((f2_){lo, hi}, bf16x2n_t); return __builtin_bit_cast(unsigned, b); }
; __device__ __forceinline__ float gate_u8(unsigned w, int k) { return __builtin_fmaf((float)((w >> (8 * k)) & 0xffu), 1.0f / 255.0f, 0.5f / 255.0f); }
;     __device__ __forceinline__ void operator()(const f32x4 (&acc)[2][2][4][2], const pg8::Unit& u, int wr, int wc, int fr, int fq) const {
;     ...
;         for (int ai = 0; ai < 2; ++ai)
; #pragma unroll
;             for (int m = 0; m < 4; ++m) { const int r = row0 + ai * 128 + m * 16;
; #pragma unroll
;                 for (int bj = 0; bj < 2; ++bj) { const u32x2 g = gg[ai][m][bj];
;                     const f32x4 v0 = acc[ai][bj][m][0] * (1.0f / 32.0f), v1 = acc[ai][bj][m][1] * (1.0f / 32.0f);
;                     u32x4 w; w.x = pk2(v0[0] * gate_u8(g.x, 0), v0[1] * gate_u8(g.x, 1)); w.y = pk2(v0[2] * gate_u8(g.x, 2), v0[3] * gate_u8(g.x, 3)); w.z = pk2(v1[0] * gate_u8(g.y, 0), v1[1] * gate_u8(g.y, 1)); w.w = pk2(v1[2] * gate_u8(g.y, 2), v1[3] * gate_u8(g.y, 3));
	s_mov_b32 s26, 0x3d000000
	v_pk_mul_f32 v[148:149], v[126:127], s[26:27] op_sel_hi:[1,0]
	v_pk_mul_f32 v[156:157], v[124:125], s[26:27] op_sel_hi:[1,0]
	v_pk_mul_f32 v[152:153], v[122:123], s[26:27] op_sel_hi:[1,0]
	v_pk_mul_f32 v[154:155], v[120:121], s[26:27] op_sel_hi:[1,0]
	v_pk_mul_f32 v[126:127], v[110:111], s[26:27] op_sel_hi:[1,0]
	v_pk_mul_f32 v[130:131], v[108:109], s[26:27] op_sel_hi:[1,0]
	v_pk_mul_f32 v[124:125], v[102:103], s[26:27] op_sel_hi:[1,0]
	v_pk_mul_f32 v[128:129], v[100:101], s[26:27] op_sel_hi:[1,0]
	v_pk_mul_f32 v[118:119], v[118:119], s[26:27] op_sel_hi:[1,0]
	v_pk_mul_f32 v[122:123], v[116:117], s[26:27] op_sel_hi:[1,0]
	v_pk_mul_f32 v[110:111], v[114:115], s[26:27] op_sel_hi:[1,0]
	v_pk_mul_f32 v[116:117], v[112:113], s[26:27] op_sel_hi:[1,0]
	v_pk_mul_f32 v[112:113], v[94:95], s[26:27] op_sel_hi:[1,0]
	v_pk_mul_f32 v[120:121], v[92:93], s[26:27] op_sel_hi:[1,0]
	v_pk_mul_f32 v[108:109], v[86:87], s[26:27] op_sel_hi:[1,0]
	v_pk_mul_f32 v[114:115], v[84:85], s[26:27] op_sel_hi:[1,0]
	v_pk_mul_f32 v[100:101], v[106:107], s[26:27] op_sel_hi:[1,0]
	v_pk_mul_f32 v[106:107], v[104:105], s[26:27] op_sel_hi:[1,0]
	v_pk_mul_f32 v[94:95], v[98:99], s[26:27] op_sel_hi:[1,0]
	v_pk_mul_f32 v[102:103], v[96:97], s[26:27] op_sel_hi:[1,0]
	v_pk_mul_f32 v[96:97], v[78:79], s[26:27] op_sel_hi:[1,0]
	v_pk_mul_f32 v[104:105], v[76:77], s[26:27] op_sel_hi:[1,0]
	v_pk_mul_f32 v[92:93], v[74:75], s[26:27] op_sel_hi:[1,0]
	v_pk_mul_f32 v[98:99], v[72:73], s[26:27] op_sel_hi:[1,0]
	v_pk_mul_f32 v[84:85], v[90:91], s[26:27] op_sel_hi:[1,0]
	v_pk_mul_f32 v[90:91], v[88:89], s[26:27] op_sel_hi:[1,0]
	v_pk_mul_f32 v[78:79], v[82:83], s[26:27] op_sel_hi:[1,0]
	v_pk_mul_f32 v[86:87], v[80:81], s[26:27] op_sel_hi:[1,0]
	v_pk_mul_f32 v[80:81], v[70:71], s[26:27] op_sel_hi:[1,0]
	v_pk_mul_f32 v[88:89], v[68:69], s[26:27] op_sel_hi:[1,0]
	v_pk_mul_f32 v[76:77], v[62:63], s[26:27] op_sel_hi:[1,0]
	v_pk_mul_f32 v[82:83], v[60:61], s[26:27] op_sel_hi:[1,0]
	v_pk_mul_f32 v[68:69], v[66:67], s[26:27] op_sel_hi:[1,0]
	v_pk_mul_f32 v[74:75], v[64:65], s[26:27] op_sel_hi:[1,0]
	v_pk_mul_f32 v[62:63], v[58:59], s[26:27] op_sel_hi:[1,0]
	v_pk_mul_f32 v[70:71], v[56:57], s[26:27] op_sel_hi:[1,0]
	v_pk_mul_f32 v[64:65], v[46:47], s[26:27] op_sel_hi:[1,0]
	v_pk_mul_f32 v[72:73], v[44:45], s[26:27] op_sel_hi:[1,0]
	v_pk_mul_f32 v[60:61], v[38:39], s[26:27] op_sel_hi:[1,0]
	v_pk_mul_f32 v[66:67], v[36:37], s[26:27] op_sel_hi:[1,0]
	v_pk_mul_f32 v[54:55], v[54:55], s[26:27] op_sel_hi:[1,0]
	v_pk_mul_f32 v[58:59], v[52:53], s[26:27] op_sel_hi:[1,0]
	v_pk_mul_f32 v[46:47], v[50:51], s[26:27] op_sel_hi:[1,0]
	v_pk_mul_f32 v[52:53], v[48:49], s[26:27] op_sel_hi:[1,0]
	v_pk_mul_f32 v[48:49], v[30:31], s[26:27] op_sel_hi:[1,0]
	v_pk_mul_f32 v[56:57], v[28:29], s[26:27] op_sel_hi:[1,0]
	v_pk_mul_f32 v[44:45], v[22:23], s[26:27] op_sel_hi:[1,0]
	v_pk_mul_f32 v[50:51], v[20:21], s[26:27] op_sel_hi:[1,0]
	v_pk_mul_f32 v[36:37], v[42:43], s[26:27] op_sel_hi:[1,0]
	v_pk_mul_f32 v[40:41], v[40:41], s[26:27] op_sel_hi:[1,0]
	v_pk_mul_f32 v[28:29], v[34:35], s[26:27] op_sel_hi:[1,0]
	v_pk_mul_f32 v[34:35], v[32:33], s[26:27] op_sel_hi:[1,0]
	v_pk_mul_f32 v[30:31], v[14:15], s[26:27] op_sel_hi:[1,0]
	v_pk_mul_f32 v[38:39], v[12:13], s[26:27] op_sel_hi:[1,0]
	v_pk_mul_f32 v[22:23], v[10:11], s[26:27] op_sel_hi:[1,0]
	v_pk_mul_f32 v[32:33], v[8:9], s[26:27] op_sel_hi:[1,0]
	v_pk_mul_f32 v[12:13], v[26:27], s[26:27] op_sel_hi:[1,0]
	v_pk_mul_f32 v[20:21], v[24:25], s[26:27] op_sel_hi:[1,0]
	v_pk_mul_f32 v[8:9], v[18:19], s[26:27] op_sel_hi:[1,0]
	v_pk_mul_f32 v[14:15], v[16:17], s[26:27] op_sel_hi:[1,0]
	v_pk_mul_f32 v[6:7], v[6:7], s[26:27] op_sel_hi:[1,0]
	v_pk_mul_f32 v[16:17], v[4:5], s[26:27] op_sel_hi:[1,0]
	v_pk_mul_f32 v[4:5], v[2:3], s[26:27] op_sel_hi:[1,0]
	v_pk_mul_f32 v[10:11], v[0:1], s[26:27] op_sel_hi:[1,0]
	v_mov_b32_e32 v232, v181
	v_mov_b32_e32 v233, v223
	v_mov_b32_e32 v223, 0x260
	v_mov_b32_e32 v234, 0x1e000
	v_mov_b32_e32 v235, 0x7f800000
	v_mov_b32_e32 v236, 0x7fc00000
	v_mov_b32_e32 v237, 0x7fffff
	v_mov_b64_e32 v[238:239], 0x140
	v_mov_b64_e32 v[252:253], 0x13f
	v_mov_b32_e32 v198, 23

; #define PG8_STAGE(bufoff, gbase, voff) do { _Pragma("unroll") for (int _i = 0; _i < 2; ++_i) \
;         { unsigned vo_ = (voff) + _i * voff##_d; asm volatile("" : "+v"(vo_)); __builtin_amdgcn_global_load_lds((const unsigned*)((const char*)(gbase) + vo_), (PG8_LAS unsigned*)(lds + (bufoff) + ldsw + _i * 8192), 16, 0, 0); } } while (0)
; #define PG8_LDA(dst, b, h) do { _Pragma("unroll") for (int m = 0; m < 4; ++m) _Pragma("unroll") for (int k = 0; k < 2; ++k) dst[m][k] = *(const PG8_LAS bf16x8*)(lds + PG8_SA(b, h) + aoff + m * 2048 + k * 1024); } while (0)
; #define PG8_LDB(dst, b, h) do { _Pragma("unroll") for (int n = 0; n < 2; ++n) _Pragma("unroll") for (int k = 0; k < 2; ++k) dst[n][k] = *(const PG8_LAS bf16x8*)(lds + PG8_SB(b, h) + boff + n * 2048 + k * 1024); } while (0)
; template <class Epi, class Sched, bool ALIGN_EPI, bool F8 = false>
; __device__ __forceinline__ void gemm_phase(PG8_LAS unsigned char* lds, const Gemm g, const Sched& S, const Epi& E, const int wid) {
;     ...
;         for (int t = 0; t < nt; t += 2) {
;             const bool last = (t == nt - 2);
;             const char* a1 = cA + (size_t)(t + 1) * kstep;
;             const char* a2 = last ? nA : cA + (size_t)(t + 2) * kstep; const char* b2 = last ? nB : cB + (size_t)(t + 2) * kstep;
;             const char* a3 = a2 + kstep; const char* b3 = b2 + kstep;
;             PG8_LDB(B0, 0, 0); PG8_LDB(B1, 0, 1); PG8_SCHED; PG8_LDA(At, 0, 0); PG8_STAGE(PG8_SA(1, 1), a1 + hA, voffA);
;             PG8_WAIT_V(8); PG8_WAIT_L(0); PG8_BAR; PG8_MMA(0, 0, At, B0); PG8_MMA(0, 1, At, B1); PG8_BAR; PG8_SCHED;
;             PG8_LDA(At, 0, 1); PG8_STAGE(PG8_SB(0, 0), b2, voffB); PG8_STAGE(PG8_SB(0, 1), b2 + hB, voffB); PG8_STAGE(PG8_SA(0, 0), a2, voffA);
;             PG8_WAIT_V(8); PG8_WAIT_L(0); PG8_BAR; PG8_MMA(1, 0, At, B0); PG8_MMA(1, 1, At, B1); PG8_BAR; PG8_SCHED;
;             PG8_LDB(B0, 1, 0); PG8_LDB(B1, 1, 1); PG8_SCHED; PG8_LDA(At, 1, 0); PG8_STAGE(PG8_SA(0, 1), a2 + hA, voffA);
;             PG8_WAIT_V(8); PG8_WAIT_L(0); PG8_BAR; PG8_MMA(0, 0, At, B0); PG8_MMA(0, 1, At, B1); PG8_BAR; PG8_SCHED;
;             PG8_LDA(At, 1, 1); PG8_STAGE(PG8_SB(1, 0), b3, voffB); PG8_STAGE(PG8_SB(1, 1), b3 + hB, voffB); PG8_STAGE(PG8_SA(1, 0), a3, voffA);
;             PG8_WAIT_V(8); PG8_WAIT_L(0); PG8_BAR; PG8_MMA(1, 0, At, B0); PG8_MMA(1, 1, At, B1); PG8_BAR; PG8_SCHED;
;         }
.LBB0_1851:
	s_add_i32 s76, s48, 2
	s_add_u32 s50, s46, 0xfff80080
	s_addc_u32 s49, s47, -1
	s_add_i32 s77, 0, 0x10000
	s_cmp_eq_u32 s69, s48
	s_cselect_b32 s49, s23, s49
	s_cselect_b32 s48, s25, s50
	s_cselect_b32 s51, s72, s75
	s_cselect_b32 s50, s73, s74
	s_add_i32 s80, 0, 0x14000
	v_add_u32_e32 v140, s77, v243
	v_add_u32_e32 v156, s80, v243
	ds_read_b128 v[128:131], v140
	ds_read_b128 v[132:135], v140 offset:1024
	ds_read_b128 v[136:139], v140 offset:2048
	ds_read_b128 v[140:143], v140 offset:3072
	ds_read_b128 v[144:147], v156
	ds_read_b128 v[148:151], v156 offset:1024
	ds_read_b128 v[152:155], v156 offset:2048
	ds_read_b128 v[156:159], v156 offset:3072
	ds_read_b128 v[160:163], v244
	ds_read_b128 v[164:167], v244 offset:1024
	ds_read_b128 v[168:171], v244 offset:2048
	ds_read_b128 v[174:177], v244 offset:3072
	ds_read_b128 v[178:181], v244 offset:4096
	ds_read_b128 v[182:185], v244 offset:5120
	ds_read_b128 v[186:189], v244 offset:6144
	ds_read_b128 v[190:193], v244 offset:7168
	s_add_i32 m0, s60, 0xc000
	s_nop 0
	global_load_lds_dwordx4 v173, s[46:47]
	s_add_i32 m0, s60, 0xe000
	s_nop 0
	global_load_lds_dwordx4 v242, s[46:47]
	s_waitcnt vmcnt(8)
	s_waitcnt lgkmcnt(0)
	s_barrier
	s_setprio 1
	s_waitcnt lgkmcnt(0)
	v_mfma_f32_16x16x32_bf16 v[124:127], v[128:131], v[160:163], v[124:127]
	v_mfma_f32_16x16x32_bf16 v[120:123], v[136:139], v[160:163], v[120:123]
	v_mfma_f32_16x16x32_bf16 v[108:111], v[128:131], v[168:171], v[108:111]
	v_mfma_f32_16x16x32_bf16 v[104:107], v[136:139], v[168:171], v[104:107]
	v_mfma_f32_16x16x32_bf16 v[92:95], v[128:131], v[178:181], v[92:95]
	v_mfma_f32_16x16x32_bf16 v[88:91], v[136:139], v[178:181], v[88:91]
	v_mfma_f32_16x16x32_bf16 v[76:79], v[128:131], v[186:189], v[76:79]
	v_mfma_f32_16x16x32_bf16 v[72:75], v[136:139], v[186:189], v[72:75]
	v_mfma_f32_16x16x32_bf16 v[124:127], v[132:135], v[164:167], v[124:127]
	v_mfma_f32_16x16x32_bf16 v[120:123], v[140:143], v[164:167], v[120:123]
	v_mfma_f32_16x16x32_bf16 v[108:111], v[132:135], v[174:177], v[108:111]
	v_mfma_f32_16x16x32_bf16 v[104:107], v[140:143], v[174:177], v[104:107]
	v_mfma_f32_16x16x32_bf16 v[92:95], v[132:135], v[182:185], v[92:95]
	v_mfma_f32_16x16x32_bf16 v[88:91], v[140:143], v[182:185], v[88:91]
	v_mfma_f32_16x16x32_bf16 v[76:79], v[132:135], v[190:193], v[76:79]
	v_mfma_f32_16x16x32_bf16 v[72:75], v[140:143], v[190:193], v[72:75]
	s_setprio 0
	s_setprio 1
	v_mfma_f32_16x16x32_bf16 v[116:119], v[144:147], v[160:163], v[116:119]
	v_mfma_f32_16x16x32_bf16 v[112:115], v[152:155], v[160:163], v[112:115]
	v_mfma_f32_16x16x32_bf16 v[100:103], v[144:147], v[168:171], v[100:103]
	v_mfma_f32_16x16x32_bf16 v[96:99], v[152:155], v[168:171], v[96:99]
	v_mfma_f32_16x16x32_bf16 v[84:87], v[144:147], v[178:181], v[84:87]
	v_mfma_f32_16x16x32_bf16 v[80:83], v[152:155], v[178:181], v[80:83]
	v_mfma_f32_16x16x32_bf16 v[68:71], v[144:147], v[186:189], v[68:71]
	v_mfma_f32_16x16x32_bf16 v[64:67], v[152:155], v[186:189], v[64:67]
	v_mfma_f32_16x16x32_bf16 v[116:119], v[148:151], v[164:167], v[116:119]
	v_mfma_f32_16x16x32_bf16 v[112:115], v[156:159], v[164:167], v[112:115]
	v_mfma_f32_16x16x32_bf16 v[100:103], v[148:151], v[174:177], v[100:103]
	v_mfma_f32_16x16x32_bf16 v[96:99], v[156:159], v[174:177], v[96:99]
	v_mfma_f32_16x16x32_bf16 v[84:87], v[148:151], v[182:185], v[84:87]
	v_mfma_f32_16x16x32_bf16 v[80:83], v[156:159], v[182:185], v[80:83]
	v_mfma_f32_16x16x32_bf16 v[68:71], v[148:151], v[190:193], v[68:71]
	v_mfma_f32_16x16x32_bf16 v[64:67], v[156:159], v[190:193], v[64:67]
	s_setprio 0
	s_barrier
	s_add_i32 s77, s77, s58
	ds_read_b128 v[160:163], v244 offset:16384
	ds_read_b128 v[164:167], v244 offset:17408
	ds_read_b128 v[168:171], v244 offset:18432
	ds_read_b128 v[174:177], v244 offset:19456
	ds_read_b128 v[178:181], v244 offset:20480
	ds_read_b128 v[182:185], v244 offset:21504
	ds_read_b128 v[186:189], v244 offset:22528
	ds_read_b128 v[190:193], v244 offset:23552
	s_mov_b32 m0, s77
	s_nop 0
	global_load_lds_dwordx4 v173, s[50:51]
	s_add_i32 m0, s77, 0x2000
	s_add_u32 s78, s50, 0x80000
	global_load_lds_dwordx4 v242, s[50:51]
	s_addc_u32 s79, s51, 0
	s_add_i32 s77, s80, s58
	s_mov_b32 m0, s77
	s_nop 0
	global_load_lds_dwordx4 v173, s[78:79]
	s_add_i32 m0, s77, 0x2000
	s_nop 0
	global_load_lds_dwordx4 v242, s[78:79]
	s_mov_b32 m0, s60
	s_nop 0
	global_load_lds_dwordx4 v173, s[48:49]
	s_mov_b32 m0, s61
	s_nop 0
	global_load_lds_dwordx4 v242, s[48:49]
	s_waitcnt vmcnt(8)
	s_waitcnt lgkmcnt(0)
	s_barrier
	s_setprio 1
	s_waitcnt lgkmcnt(0)
	v_mfma_f32_16x16x32_bf16 v[60:63], v[128:131], v[160:163], v[60:63]
	v_mfma_f32_16x16x32_bf16 v[56:59], v[136:139], v[160:163], v[56:59]
	v_mfma_f32_16x16x32_bf16 v[44:47], v[128:131], v[168:171], v[44:47]
	v_mfma_f32_16x16x32_bf16 v[40:43], v[136:139], v[168:171], v[40:43]
	v_mfma_f32_16x16x32_bf16 v[28:31], v[128:131], v[178:181], v[28:31]
	v_mfma_f32_16x16x32_bf16 v[24:27], v[136:139], v[178:181], v[24:27]
	v_mfma_f32_16x16x32_bf16 v[12:15], v[128:131], v[186:189], v[12:15]
	v_mfma_f32_16x16x32_bf16 v[8:11], v[136:139], v[186:189], v[8:11]
	v_mfma_f32_16x16x32_bf16 v[60:63], v[132:135], v[164:167], v[60:63]
	v_mfma_f32_16x16x32_bf16 v[56:59], v[140:143], v[164:167], v[56:59]
	v_mfma_f32_16x16x32_bf16 v[44:47], v[132:135], v[174:177], v[44:47]
	v_mfma_f32_16x16x32_bf16 v[40:43], v[140:143], v[174:177], v[40:43]
	v_mfma_f32_16x16x32_bf16 v[28:31], v[132:135], v[182:185], v[28:31]
	v_mfma_f32_16x16x32_bf16 v[24:27], v[140:143], v[182:185], v[24:27]
	v_mfma_f32_16x16x32_bf16 v[12:15], v[132:135], v[190:193], v[12:15]
	v_mfma_f32_16x16x32_bf16 v[8:11], v[140:143], v[190:193], v[8:11]
	s_setprio 0
	s_setprio 1
	v_mfma_f32_16x16x32_bf16 v[52:55], v[144:147], v[160:163], v[52:55]
	v_mfma_f32_16x16x32_bf16 v[48:51], v[152:155], v[160:163], v[48:51]
	v_mfma_f32_16x16x32_bf16 v[36:39], v[144:147], v[168:171], v[36:39]
	v_mfma_f32_16x16x32_bf16 v[32:35], v[152:155], v[168:171], v[32:35]
	v_mfma_f32_16x16x32_bf16 v[20:23], v[144:147], v[178:181], v[20:23]
	v_mfma_f32_16x16x32_bf16 v[16:19], v[152:155], v[178:181], v[16:19]
	v_mfma_f32_16x16x32_bf16 v[4:7], v[144:147], v[186:189], v[4:7]
	v_mfma_f32_16x16x32_bf16 v[0:3], v[152:155], v[186:189], v[0:3]
	v_mfma_f32_16x16x32_bf16 v[52:55], v[148:151], v[164:167], v[52:55]
	v_mfma_f32_16x16x32_bf16 v[48:51], v[156:159], v[164:167], v[48:51]
	v_mfma_f32_16x16x32_bf16 v[36:39], v[148:151], v[174:177], v[36:39]
	v_mfma_f32_16x16x32_bf16 v[32:35], v[156:159], v[174:177], v[32:35]
	v_mfma_f32_16x16x32_bf16 v[20:23], v[148:151], v[182:185], v[20:23]
	v_mfma_f32_16x16x32_bf16 v[16:19], v[156:159], v[182:185], v[16:19]
	v_mfma_f32_16x16x32_bf16 v[4:7], v[148:151], v[190:193], v[4:7]
	v_mfma_f32_16x16x32_bf16 v[0:3], v[156:159], v[190:193], v[0:3]
	s_setprio 0
	s_barrier
; #define PG8_STAGE(bufoff, gbase, voff) do { _Pragma("unroll") for (int _i = 0; _i < 2; ++_i) \
;         { unsigned vo_ = (voff) + _i * voff##_d; asm volatile("" : "+v"(vo_)); __builtin_amdgcn_global_load_lds((const unsigned*)((const char*)(gbase) + vo_), (PG8_LAS unsigned*)(lds + (bufoff) + ldsw + _i * 8192), 16, 0, 0); } } while (0)
; #define PG8_LDA(dst, b, h) do { _Pragma("unroll") for (int m = 0; m < 4; ++m) _Pragma("unroll") for (int k = 0; k < 2; ++k) dst[m][k] = *(const PG8_LAS bf16x8*)(lds + PG8_SA(b, h) + aoff + m * 2048 + k * 1024); } while (0)
; #define PG8_LDB(dst, b, h) do { _Pragma("unroll") for (int n = 0; n < 2; ++n) _Pragma("unroll") for (int k = 0; k < 2; ++k) dst[n][k] = *(const PG8_LAS bf16x8*)(lds + PG8_SB(b, h) + boff + n * 2048 + k * 1024); } while (0)
; template <class Epi, class Sched, bool ALIGN_EPI, bool F8 = false>
; __device__ __forceinline__ void gemm_phase(PG8_LAS unsigned char* lds, const Gemm g, const Sched& S, const Epi& E, const int wid) {
;     ...
;         for (int t = 0; t < nt; t += 2) {
;             const bool last = (t == nt - 2);
;             const char* a1 = cA + (size_t)(t + 1) * kstep;
;             const char* a2 = last ? nA : cA + (size_t)(t + 2) * kstep; const char* b2 = last ? nB : cB + (size_t)(t + 2) * kstep;
;             const char* a3 = a2 + kstep; const char* b3 = b2 + kstep;
;             PG8_LDB(B0, 0, 0); PG8_LDB(B1, 0, 1); PG8_SCHED; PG8_LDA(At, 0, 0); PG8_STAGE(PG8_SA(1, 1), a1 + hA, voffA);
;             PG8_WAIT_V(8); PG8_WAIT_L(0); PG8_BAR; PG8_MMA(0, 0, At, B0); PG8_MMA(0, 1, At, B1); PG8_BAR; PG8_SCHED;
;             PG8_LDA(At, 0, 1); PG8_STAGE(PG8_SB(0, 0), b2, voffB); PG8_STAGE(PG8_SB(0, 1), b2 + hB, voffB); PG8_STAGE(PG8_SA(0, 0), a2, voffA);
;             PG8_WAIT_V(8); PG8_WAIT_L(0); PG8_BAR; PG8_MMA(1, 0, At, B0); PG8_MMA(1, 1, At, B1); PG8_BAR; PG8_SCHED;
;             PG8_LDB(B0, 1, 0); PG8_LDB(B1, 1, 1); PG8_SCHED; PG8_LDA(At, 1, 0); PG8_STAGE(PG8_SA(0, 1), a2 + hA, voffA);
;             PG8_WAIT_V(8); PG8_WAIT_L(0); PG8_BAR; PG8_MMA(0, 0, At, B0); PG8_MMA(0, 1, At, B1); PG8_BAR; PG8_SCHED;
;             PG8_LDA(At, 1, 1); PG8_STAGE(PG8_SB(1, 0), b3, voffB); PG8_STAGE(PG8_SB(1, 1), b3 + hB, voffB); PG8_STAGE(PG8_SA(1, 0), a3, voffA);
;             PG8_WAIT_V(8); PG8_WAIT_L(0); PG8_BAR; PG8_MMA(1, 0, At, B0); PG8_MMA(1, 1, At, B1); PG8_BAR; PG8_SCHED;
;         }
	s_add_i32 s77, 0, 0x18000
	s_add_i32 s80, 0, 0x1c000
	v_add_u32_e32 v140, s77, v243
	v_add_u32_e32 v156, s80, v243
	ds_read_b128 v[128:131], v140
	ds_read_b128 v[132:135], v140 offset:1024
	ds_read_b128 v[136:139], v140 offset:2048
	ds_read_b128 v[140:143], v140 offset:3072
	ds_read_b128 v[144:147], v156
	ds_read_b128 v[148:151], v156 offset:1024
	ds_read_b128 v[152:155], v156 offset:2048
	ds_read_b128 v[156:159], v156 offset:3072
	s_add_u32 s78, s48, 0x80000
	s_mov_b32 m0, s62
	ds_read_b128 v[160:163], v244 offset:32768
	ds_read_b128 v[164:167], v244 offset:33792
	ds_read_b128 v[168:171], v244 offset:34816
	ds_read_b128 v[174:177], v244 offset:35840
	ds_read_b128 v[178:181], v244 offset:36864
	ds_read_b128 v[182:185], v244 offset:37888
	ds_read_b128 v[186:189], v244 offset:38912
	ds_read_b128 v[190:193], v244 offset:39936
	s_addc_u32 s79, s49, 0
	s_nop 0
	global_load_lds_dwordx4 v173, s[78:79]
	s_mov_b32 m0, s63
	s_nop 0
	global_load_lds_dwordx4 v242, s[78:79]
	s_waitcnt vmcnt(8)
	s_waitcnt lgkmcnt(0)
	s_barrier
	s_setprio 1
	s_waitcnt lgkmcnt(0)
	v_mfma_f32_16x16x32_bf16 v[124:127], v[128:131], v[160:163], v[124:127]
	v_mfma_f32_16x16x32_bf16 v[120:123], v[136:139], v[160:163], v[120:123]
	v_mfma_f32_16x16x32_bf16 v[108:111], v[128:131], v[168:171], v[108:111]
	v_mfma_f32_16x16x32_bf16 v[104:107], v[136:139], v[168:171], v[104:107]
	v_mfma_f32_16x16x32_bf16 v[92:95], v[128:131], v[178:181], v[92:95]
	v_mfma_f32_16x16x32_bf16 v[88:91], v[136:139], v[178:181], v[88:91]
	v_mfma_f32_16x16x32_bf16 v[76:79], v[128:131], v[186:189], v[76:79]
	v_mfma_f32_16x16x32_bf16 v[72:75], v[136:139], v[186:189], v[72:75]
	v_mfma_f32_16x16x32_bf16 v[124:127], v[132:135], v[164:167], v[124:127]
	v_mfma_f32_16x16x32_bf16 v[120:123], v[140:143], v[164:167], v[120:123]
	v_mfma_f32_16x16x32_bf16 v[108:111], v[132:135], v[174:177], v[108:111]
	v_mfma_f32_16x16x32_bf16 v[104:107], v[140:143], v[174:177], v[104:107]
	v_mfma_f32_16x16x32_bf16 v[92:95], v[132:135], v[182:185], v[92:95]
	v_mfma_f32_16x16x32_bf16 v[88:91], v[140:143], v[182:185], v[88:91]
	v_mfma_f32_16x16x32_bf16 v[76:79], v[132:135], v[190:193], v[76:79]
	v_mfma_f32_16x16x32_bf16 v[72:75], v[140:143], v[190:193], v[72:75]
	s_setprio 0
	s_setprio 1
	v_mfma_f32_16x16x32_bf16 v[116:119], v[144:147], v[160:163], v[116:119]
	v_mfma_f32_16x16x32_bf16 v[112:115], v[152:155], v[160:163], v[112:115]
	v_mfma_f32_16x16x32_bf16 v[100:103], v[144:147], v[168:171], v[100:103]
	v_mfma_f32_16x16x32_bf16 v[96:99], v[152:155], v[168:171], v[96:99]
	v_mfma_f32_16x16x32_bf16 v[84:87], v[144:147], v[178:181], v[84:87]
	v_mfma_f32_16x16x32_bf16 v[80:83], v[152:155], v[178:181], v[80:83]
	v_mfma_f32_16x16x32_bf16 v[68:71], v[144:147], v[186:189], v[68:71]
	v_mfma_f32_16x16x32_bf16 v[64:67], v[152:155], v[186:189], v[64:67]
	v_mfma_f32_16x16x32_bf16 v[116:119], v[148:151], v[164:167], v[116:119]
	v_mfma_f32_16x16x32_bf16 v[112:115], v[156:159], v[164:167], v[112:115]
	v_mfma_f32_16x16x32_bf16 v[100:103], v[148:151], v[174:177], v[100:103]
	v_mfma_f32_16x16x32_bf16 v[96:99], v[156:159], v[174:177], v[96:99]
	v_mfma_f32_16x16x32_bf16 v[84:87], v[148:151], v[182:185], v[84:87]
	v_mfma_f32_16x16x32_bf16 v[80:83], v[156:159], v[182:185], v[80:83]
	v_mfma_f32_16x16x32_bf16 v[68:71], v[148:151], v[190:193], v[68:71]
	v_mfma_f32_16x16x32_bf16 v[64:67], v[156:159], v[190:193], v[64:67]
	s_setprio 0
	s_barrier
; #define PG8_STAGE(bufoff, gbase, voff) do { _Pragma("unroll") for (int _i = 0; _i < 2; ++_i) \
;         { unsigned vo_ = (voff) + _i * voff##_d; asm volatile("" : "+v"(vo_)); __builtin_amdgcn_global_load_lds((const unsigned*)((const char*)(gbase) + vo_), (PG8_LAS unsigned*)(lds + (bufoff) + ldsw + _i * 8192), 16, 0, 0); } } while (0)
; #define PG8_LDA(dst, b, h) do { _Pragma("unroll") for (int m = 0; m < 4; ++m) _Pragma("unroll") for (int k = 0; k < 2; ++k) dst[m][k] = *(const PG8_LAS bf16x8*)(lds + PG8_SA(b, h) + aoff + m * 2048 + k * 1024); } while (0)
; #define PG8_LDB(dst, b, h) do { _Pragma("unroll") for (int n = 0; n < 2; ++n) _Pragma("unroll") for (int k = 0; k < 2; ++k) dst[n][k] = *(const PG8_LAS bf16x8*)(lds + PG8_SB(b, h) + boff + n * 2048 + k * 1024); } while (0)
; template <class Epi, class Sched, bool ALIGN_EPI, bool F8 = false>
; __device__ __forceinline__ void gemm_phase(PG8_LAS unsigned char* lds, const Gemm g, const Sched& S, const Epi& E, const int wid) {
;     ...
;         for (int t = 0; t < nt; t += 2) {
;             const bool last = (t == nt - 2);
;             const char* a1 = cA + (size_t)(t + 1) * kstep;
;             const char* a2 = last ? nA : cA + (size_t)(t + 2) * kstep; const char* b2 = last ? nB : cB + (size_t)(t + 2) * kstep;
;             const char* a3 = a2 + kstep; const char* b3 = b2 + kstep;
;             PG8_LDB(B0, 0, 0); PG8_LDB(B1, 0, 1); PG8_SCHED; PG8_LDA(At, 0, 0); PG8_STAGE(PG8_SA(1, 1), a1 + hA, voffA);
;             PG8_WAIT_V(8); PG8_WAIT_L(0); PG8_BAR; PG8_MMA(0, 0, At, B0); PG8_MMA(0, 1, At, B1); PG8_BAR; PG8_SCHED;
;             PG8_LDA(At, 0, 1); PG8_STAGE(PG8_SB(0, 0), b2, voffB); PG8_STAGE(PG8_SB(0, 1), b2 + hB, voffB); PG8_STAGE(PG8_SA(0, 0), a2, voffA);
;             PG8_WAIT_V(8); PG8_WAIT_L(0); PG8_BAR; PG8_MMA(1, 0, At, B0); PG8_MMA(1, 1, At, B1); PG8_BAR; PG8_SCHED;
;             PG8_LDB(B0, 1, 0); PG8_LDB(B1, 1, 1); PG8_SCHED; PG8_LDA(At, 1, 0); PG8_STAGE(PG8_SA(0, 1), a2 + hA, voffA);
;             PG8_WAIT_V(8); PG8_WAIT_L(0); PG8_BAR; PG8_MMA(0, 0, At, B0); PG8_MMA(0, 1, At, B1); PG8_BAR; PG8_SCHED;
;             PG8_LDA(At, 1, 1); PG8_STAGE(PG8_SB(1, 0), b3, voffB); PG8_STAGE(PG8_SB(1, 1), b3 + hB, voffB); PG8_STAGE(PG8_SA(1, 0), a3, voffA);
;             PG8_WAIT_V(8); PG8_WAIT_L(0); PG8_BAR; PG8_MMA(1, 0, At, B0); PG8_MMA(1, 1, At, B1); PG8_BAR; PG8_SCHED;
;         }
	ds_read_b128 v[160:163], v244 offset:49152
	ds_read_b128 v[164:167], v244 offset:50176
	ds_read_b128 v[168:171], v244 offset:51200
	ds_read_b128 v[174:177], v244 offset:52224
	ds_read_b128 v[178:181], v244 offset:53248
	ds_read_b128 v[182:185], v244 offset:54272
	ds_read_b128 v[186:189], v244 offset:55296
	ds_read_b128 v[190:193], v244 offset:56320
	s_add_i32 s77, s77, s58
	s_add_u32 s100, s50, s2
	s_addc_u32 s101, s51, s3
	s_mov_b32 m0, s77
	s_nop 0
	global_load_lds_dwordx4 v173, s[100:101]
	s_add_i32 m0, s77, 0x2000
	s_add_u32 s100, s50, s2
	s_addc_u32 s101, s51, s3
	s_add_u32 s50, s50, 0x80080
	global_load_lds_dwordx4 v242, s[100:101]
	s_addc_u32 s51, s51, 0
	s_add_i32 s77, s80, s58
	s_mov_b32 m0, s77
	s_nop 0
	global_load_lds_dwordx4 v173, s[50:51]
	s_add_i32 m0, s77, 0x2000
	s_nop 0
	global_load_lds_dwordx4 v242, s[50:51]
	s_mov_b32 m0, s67
	s_add_u32 s100, s48, s2
	s_addc_u32 s101, s49, s3
	global_load_lds_dwordx4 v173, s[100:101]
	s_mov_b32 m0, s68
	s_add_u32 s100, s48, s2
	s_addc_u32 s101, s49, s3
	global_load_lds_dwordx4 v242, s[100:101]
	s_waitcnt vmcnt(8)
	s_waitcnt lgkmcnt(0)
	s_barrier
	s_setprio 1
	s_waitcnt lgkmcnt(0)
	v_mfma_f32_16x16x32_bf16 v[60:63], v[128:131], v[160:163], v[60:63]
	v_mfma_f32_16x16x32_bf16 v[56:59], v[136:139], v[160:163], v[56:59]
	v_mfma_f32_16x16x32_bf16 v[44:47], v[128:131], v[168:171], v[44:47]
	v_mfma_f32_16x16x32_bf16 v[40:43], v[136:139], v[168:171], v[40:43]
	v_mfma_f32_16x16x32_bf16 v[28:31], v[128:131], v[178:181], v[28:31]
	v_mfma_f32_16x16x32_bf16 v[24:27], v[136:139], v[178:181], v[24:27]
	v_mfma_f32_16x16x32_bf16 v[12:15], v[128:131], v[186:189], v[12:15]
	v_mfma_f32_16x16x32_bf16 v[8:11], v[136:139], v[186:189], v[8:11]
	v_mfma_f32_16x16x32_bf16 v[60:63], v[132:135], v[164:167], v[60:63]
	v_mfma_f32_16x16x32_bf16 v[56:59], v[140:143], v[164:167], v[56:59]
	v_mfma_f32_16x16x32_bf16 v[44:47], v[132:135], v[174:177], v[44:47]
	v_mfma_f32_16x16x32_bf16 v[40:43], v[140:143], v[174:177], v[40:43]
	v_mfma_f32_16x16x32_bf16 v[28:31], v[132:135], v[182:185], v[28:31]
	v_mfma_f32_16x16x32_bf16 v[24:27], v[140:143], v[182:185], v[24:27]
	v_mfma_f32_16x16x32_bf16 v[12:15], v[132:135], v[190:193], v[12:15]
	v_mfma_f32_16x16x32_bf16 v[8:11], v[140:143], v[190:193], v[8:11]
	s_setprio 0
	s_setprio 1
	v_mfma_f32_16x16x32_bf16 v[52:55], v[144:147], v[160:163], v[52:55]
	v_mfma_f32_16x16x32_bf16 v[48:51], v[152:155], v[160:163], v[48:51]
	v_mfma_f32_16x16x32_bf16 v[36:39], v[144:147], v[168:171], v[36:39]
	v_mfma_f32_16x16x32_bf16 v[32:35], v[152:155], v[168:171], v[32:35]
	v_mfma_f32_16x16x32_bf16 v[20:23], v[144:147], v[178:181], v[20:23]
	v_mfma_f32_16x16x32_bf16 v[16:19], v[152:155], v[178:181], v[16:19]
	v_mfma_f32_16x16x32_bf16 v[4:7], v[144:147], v[186:189], v[4:7]
	v_mfma_f32_16x16x32_bf16 v[0:3], v[152:155], v[186:189], v[0:3]
	v_mfma_f32_16x16x32_bf16 v[52:55], v[148:151], v[164:167], v[52:55]
	v_mfma_f32_16x16x32_bf16 v[48:51], v[156:159], v[164:167], v[48:51]
	v_mfma_f32_16x16x32_bf16 v[36:39], v[148:151], v[174:177], v[36:39]
	v_mfma_f32_16x16x32_bf16 v[32:35], v[156:159], v[174:177], v[32:35]
	v_mfma_f32_16x16x32_bf16 v[20:23], v[148:151], v[182:185], v[20:23]
	v_mfma_f32_16x16x32_bf16 v[16:19], v[156:159], v[182:185], v[16:19]
	v_mfma_f32_16x16x32_bf16 v[4:7], v[148:151], v[190:193], v[4:7]
	v_mfma_f32_16x16x32_bf16 v[0:3], v[156:159], v[190:193], v[0:3]
	s_setprio 0
	s_barrier
	s_add_u32 s46, s46, 0x100
	s_addc_u32 s47, s47, 0
	s_add_u32 s74, s74, 0x100
	s_addc_u32 s75, s75, 0
	s_cmp_ge_i32 s76, s64
	s_mov_b32 s48, s76
	s_cbranch_scc0 .LBB0_1851
	s_mov_b32 s76, 0x28000
	s_mov_b32 s75, 0x30000
	s_mov_b32 s72, 0x80000
	s_mov_b32 s73, 0x90000
	s_mov_b32 s74, 0xa0000
	s_mov_b32 s77, 0x3f400000
	s_mov_b32 s78, 0x3fa00000
	s_mov_b32 s79, 0x3fe00000
	s_mov_b32 s80, 0x40600000

; #define PG8_STAGE(bufoff, gbase, voff) do { _Pragma("unroll") for (int _i = 0; _i < 2; ++_i) \
;         { unsigned vo_ = (voff) + _i * voff##_d; asm volatile("" : "+v"(vo_)); __builtin_amdgcn_global_load_lds((const unsigned*)((const char*)(gbase) + vo_), (PG8_LAS unsigned*)(lds + (bufoff) + ldsw + _i * 8192), 16, 0, 0); } } while (0)
; #define PG8_LDA(dst, b, h) do { _Pragma("unroll") for (int m = 0; m < 4; ++m) _Pragma("unroll") for (int k = 0; k < 2; ++k) dst[m][k] = *(const PG8_LAS bf16x8*)(lds + PG8_SA(b, h) + aoff + m * 2048 + k * 1024); } while (0)
; #define PG8_LDB(dst, b, h) do { _Pragma("unroll") for (int n = 0; n < 2; ++n) _Pragma("unroll") for (int k = 0; k < 2; ++k) dst[n][k] = *(const PG8_LAS bf16x8*)(lds + PG8_SB(b, h) + boff + n * 2048 + k * 1024); } while (0)
; template <class Epi, class Sched, bool ALIGN_EPI, bool F8 = false>
; __device__ __forceinline__ void gemm_phase(PG8_LAS unsigned char* lds, const Gemm g, const Sched& S, const Epi& E, const int wid) {
;     ...
;         for (int t = 0; t < nt; t += 2) {
;             const bool last = (t == nt - 2);
;             const char* a1 = cA + (size_t)(t + 1) * kstep;
;             const char* a2 = last ? nA : cA + (size_t)(t + 2) * kstep; const char* b2 = last ? nB : cB + (size_t)(t + 2) * kstep;
;             const char* a3 = a2 + kstep; const char* b3 = b2 + kstep;
;             PG8_LDB(B0, 0, 0); PG8_LDB(B1, 0, 1); PG8_SCHED; PG8_LDA(At, 0, 0); PG8_STAGE(PG8_SA(1, 1), a1 + hA, voffA);
;             PG8_WAIT_V(8); PG8_WAIT_L(0); PG8_BAR; PG8_MMA(0, 0, At, B0); PG8_MMA(0, 1, At, B1); PG8_BAR; PG8_SCHED;
;             PG8_LDA(At, 0, 1); PG8_STAGE(PG8_SB(0, 0), b2, voffB); PG8_STAGE(PG8_SB(0, 1), b2 + hB, voffB); PG8_STAGE(PG8_SA(0, 0), a2, voffA);
;             PG8_WAIT_V(8); PG8_WAIT_L(0); PG8_BAR; PG8_MMA(1, 0, At, B0); PG8_MMA(1, 1, At, B1); PG8_BAR; PG8_SCHED;
;             PG8_LDB(B0, 1, 0); PG8_LDB(B1, 1, 1); PG8_SCHED; PG8_LDA(At, 1, 0); PG8_STAGE(PG8_SA(0, 1), a2 + hA, voffA);
;             PG8_WAIT_V(8); PG8_WAIT_L(0); PG8_BAR; PG8_MMA(0, 0, At, B0); PG8_MMA(0, 1, At, B1); PG8_BAR; PG8_SCHED;
;             PG8_LDA(At, 1, 1); PG8_STAGE(PG8_SB(1, 0), b3, voffB); PG8_STAGE(PG8_SB(1, 1), b3 + hB, voffB); PG8_STAGE(PG8_SA(1, 0), a3, voffA);
;             PG8_WAIT_V(8); PG8_WAIT_L(0); PG8_BAR; PG8_MMA(1, 0, At, B0); PG8_MMA(1, 1, At, B1); PG8_BAR; PG8_SCHED;
;         }
.LBB0_1990:
	s_add_i32 s66, s28, 2
	s_add_u32 s30, s26, 0xfff80080
	s_addc_u32 s29, s27, -1
	s_add_i32 s67, 0, 0x10000
	s_cmp_eq_u32 s58, s28
	s_cselect_b32 s29, s15, s29
	s_cselect_b32 s28, s17, s30
	v_add_u32_e32 v135, s67, v133
	s_cselect_b32 s31, s62, s65
	s_cselect_b32 s30, s63, s64
	s_add_i32 s70, 0, 0x14000
	ds_read_b128 v[136:139], v135
	ds_read_b128 v[140:143], v135 offset:1024
	ds_read_b128 v[144:147], v135 offset:2048
	ds_read_b128 v[148:151], v135 offset:3072
	v_add_u32_e32 v135, s70, v133
	ds_read_b128 v[152:155], v135
	ds_read_b128 v[156:159], v135 offset:1024
	ds_read_b128 v[160:163], v135 offset:2048
	ds_read_b128 v[164:167], v135 offset:3072
	ds_read_b128 v[168:171], v134
	ds_read_b128 v[172:175], v134 offset:1024
	ds_read_b128 v[176:179], v134 offset:2048
	ds_read_b128 v[180:183], v134 offset:3072
	ds_read_b128 v[184:187], v134 offset:4096
	ds_read_b128 v[188:191], v134 offset:5120
	ds_read_b128 v[192:195], v134 offset:6144
	ds_read_b128 v[196:199], v134 offset:7168
	s_add_i32 m0, s13, 0xc000
	s_nop 0
	global_load_lds_dwordx4 v129, s[26:27]
	s_add_i32 m0, s13, 0xe000
	s_nop 0
	global_load_lds_dwordx4 v132, s[26:27]
	s_waitcnt vmcnt(8)
	s_waitcnt lgkmcnt(0)
	s_barrier
	s_setprio 1
	s_waitcnt lgkmcnt(0)
	v_mfma_f32_16x16x32_bf16 v[120:123], v[136:139], v[168:171], v[120:123]
	v_mfma_f32_16x16x32_bf16 v[124:127], v[144:147], v[168:171], v[124:127]
	v_mfma_f32_16x16x32_bf16 v[108:111], v[136:139], v[176:179], v[108:111]
	v_mfma_f32_16x16x32_bf16 v[104:107], v[144:147], v[176:179], v[104:107]
	v_mfma_f32_16x16x32_bf16 v[92:95], v[136:139], v[184:187], v[92:95]
	v_mfma_f32_16x16x32_bf16 v[88:91], v[144:147], v[184:187], v[88:91]
	v_mfma_f32_16x16x32_bf16 v[76:79], v[136:139], v[192:195], v[76:79]
	v_mfma_f32_16x16x32_bf16 v[72:75], v[144:147], v[192:195], v[72:75]
	v_mfma_f32_16x16x32_bf16 v[120:123], v[140:143], v[172:175], v[120:123]
	v_mfma_f32_16x16x32_bf16 v[124:127], v[148:151], v[172:175], v[124:127]
	v_mfma_f32_16x16x32_bf16 v[108:111], v[140:143], v[180:183], v[108:111]
	v_mfma_f32_16x16x32_bf16 v[104:107], v[148:151], v[180:183], v[104:107]
	v_mfma_f32_16x16x32_bf16 v[92:95], v[140:143], v[188:191], v[92:95]
	v_mfma_f32_16x16x32_bf16 v[88:91], v[148:151], v[188:191], v[88:91]
	v_mfma_f32_16x16x32_bf16 v[76:79], v[140:143], v[196:199], v[76:79]
	v_mfma_f32_16x16x32_bf16 v[72:75], v[148:151], v[196:199], v[72:75]
	s_setprio 0
	s_setprio 1
	v_mfma_f32_16x16x32_bf16 v[116:119], v[152:155], v[168:171], v[116:119]
	v_mfma_f32_16x16x32_bf16 v[112:115], v[160:163], v[168:171], v[112:115]
	v_mfma_f32_16x16x32_bf16 v[100:103], v[152:155], v[176:179], v[100:103]
	v_mfma_f32_16x16x32_bf16 v[96:99], v[160:163], v[176:179], v[96:99]
	v_mfma_f32_16x16x32_bf16 v[84:87], v[152:155], v[184:187], v[84:87]
	v_mfma_f32_16x16x32_bf16 v[80:83], v[160:163], v[184:187], v[80:83]
	v_mfma_f32_16x16x32_bf16 v[60:63], v[152:155], v[192:195], v[60:63]
	v_mfma_f32_16x16x32_bf16 v[56:59], v[160:163], v[192:195], v[56:59]
	v_mfma_f32_16x16x32_bf16 v[116:119], v[156:159], v[172:175], v[116:119]
	v_mfma_f32_16x16x32_bf16 v[112:115], v[164:167], v[172:175], v[112:115]
	v_mfma_f32_16x16x32_bf16 v[100:103], v[156:159], v[180:183], v[100:103]
	v_mfma_f32_16x16x32_bf16 v[96:99], v[164:167], v[180:183], v[96:99]
	v_mfma_f32_16x16x32_bf16 v[84:87], v[156:159], v[188:191], v[84:87]
	v_mfma_f32_16x16x32_bf16 v[80:83], v[164:167], v[188:191], v[80:83]
	v_mfma_f32_16x16x32_bf16 v[60:63], v[156:159], v[196:199], v[60:63]
	v_mfma_f32_16x16x32_bf16 v[56:59], v[164:167], v[196:199], v[56:59]
	s_setprio 0
	s_barrier
	s_add_i32 s67, s67, s47
	ds_read_b128 v[168:171], v134 offset:16384
	ds_read_b128 v[172:175], v134 offset:17408
	ds_read_b128 v[176:179], v134 offset:18432
	ds_read_b128 v[180:183], v134 offset:19456
	ds_read_b128 v[184:187], v134 offset:20480
	ds_read_b128 v[188:191], v134 offset:21504
	ds_read_b128 v[192:195], v134 offset:22528
	ds_read_b128 v[196:199], v134 offset:23552
	s_mov_b32 m0, s67
	s_nop 0
	global_load_lds_dwordx4 v130, s[30:31]
	s_add_i32 m0, s67, 0x2000
	s_add_u32 s68, s30, 0x80000
	global_load_lds_dwordx4 v131, s[30:31]
	s_addc_u32 s69, s31, 0
	s_add_i32 s67, s70, s47
	s_mov_b32 m0, s67
	s_nop 0
	global_load_lds_dwordx4 v130, s[68:69]
	s_add_i32 m0, s67, 0x2000
	s_nop 0
	global_load_lds_dwordx4 v131, s[68:69]
	s_mov_b32 m0, s13
	s_nop 0
	global_load_lds_dwordx4 v129, s[28:29]
	s_mov_b32 m0, s49
	s_nop 0
	global_load_lds_dwordx4 v132, s[28:29]
	s_waitcnt vmcnt(8)
	s_waitcnt lgkmcnt(0)
	s_barrier
	s_setprio 1
	s_waitcnt lgkmcnt(0)
	v_mfma_f32_16x16x32_bf16 v[68:71], v[136:139], v[168:171], v[68:71]
	v_mfma_f32_16x16x32_bf16 v[64:67], v[144:147], v[168:171], v[64:67]
	v_mfma_f32_16x16x32_bf16 v[44:47], v[136:139], v[176:179], v[44:47]
	v_mfma_f32_16x16x32_bf16 v[40:43], v[144:147], v[176:179], v[40:43]
	v_mfma_f32_16x16x32_bf16 v[28:31], v[136:139], v[184:187], v[28:31]
	v_mfma_f32_16x16x32_bf16 v[24:27], v[144:147], v[184:187], v[24:27]
	v_mfma_f32_16x16x32_bf16 v[12:15], v[136:139], v[192:195], v[12:15]
	v_mfma_f32_16x16x32_bf16 v[8:11], v[144:147], v[192:195], v[8:11]
	v_mfma_f32_16x16x32_bf16 v[68:71], v[140:143], v[172:175], v[68:71]
	v_mfma_f32_16x16x32_bf16 v[64:67], v[148:151], v[172:175], v[64:67]
	v_mfma_f32_16x16x32_bf16 v[44:47], v[140:143], v[180:183], v[44:47]
	v_mfma_f32_16x16x32_bf16 v[40:43], v[148:151], v[180:183], v[40:43]
	v_mfma_f32_16x16x32_bf16 v[28:31], v[140:143], v[188:191], v[28:31]
	v_mfma_f32_16x16x32_bf16 v[24:27], v[148:151], v[188:191], v[24:27]
	v_mfma_f32_16x16x32_bf16 v[12:15], v[140:143], v[196:199], v[12:15]
	v_mfma_f32_16x16x32_bf16 v[8:11], v[148:151], v[196:199], v[8:11]
	s_setprio 0
	s_setprio 1
	v_mfma_f32_16x16x32_bf16 v[52:55], v[152:155], v[168:171], v[52:55]
	v_mfma_f32_16x16x32_bf16 v[48:51], v[160:163], v[168:171], v[48:51]
	v_mfma_f32_16x16x32_bf16 v[36:39], v[152:155], v[176:179], v[36:39]
	v_mfma_f32_16x16x32_bf16 v[32:35], v[160:163], v[176:179], v[32:35]
	v_mfma_f32_16x16x32_bf16 v[20:23], v[152:155], v[184:187], v[20:23]
	v_mfma_f32_16x16x32_bf16 v[16:19], v[160:163], v[184:187], v[16:19]
	v_mfma_f32_16x16x32_bf16 v[4:7], v[152:155], v[192:195], v[4:7]
	v_mfma_f32_16x16x32_bf16 v[0:3], v[160:163], v[192:195], v[0:3]
	v_mfma_f32_16x16x32_bf16 v[52:55], v[156:159], v[172:175], v[52:55]
	v_mfma_f32_16x16x32_bf16 v[48:51], v[164:167], v[172:175], v[48:51]
	v_mfma_f32_16x16x32_bf16 v[36:39], v[156:159], v[180:183], v[36:39]
	v_mfma_f32_16x16x32_bf16 v[32:35], v[164:167], v[180:183], v[32:35]
	v_mfma_f32_16x16x32_bf16 v[20:23], v[156:159], v[188:191], v[20:23]
	v_mfma_f32_16x16x32_bf16 v[16:19], v[164:167], v[188:191], v[16:19]
	v_mfma_f32_16x16x32_bf16 v[4:7], v[156:159], v[196:199], v[4:7]
	v_mfma_f32_16x16x32_bf16 v[0:3], v[164:167], v[196:199], v[0:3]
	s_setprio 0
	s_barrier
; #define PG8_STAGE(bufoff, gbase, voff) do { _Pragma("unroll") for (int _i = 0; _i < 2; ++_i) \
;         { unsigned vo_ = (voff) + _i * voff##_d; asm volatile("" : "+v"(vo_)); __builtin_amdgcn_global_load_lds((const unsigned*)((const char*)(gbase) + vo_), (PG8_LAS unsigned*)(lds + (bufoff) + ldsw + _i * 8192), 16, 0, 0); } } while (0)
; #define PG8_LDA(dst, b, h) do { _Pragma("unroll") for (int m = 0; m < 4; ++m) _Pragma("unroll") for (int k = 0; k < 2; ++k) dst[m][k] = *(const PG8_LAS bf16x8*)(lds + PG8_SA(b, h) + aoff + m * 2048 + k * 1024); } while (0)
; #define PG8_LDB(dst, b, h) do { _Pragma("unroll") for (int n = 0; n < 2; ++n) _Pragma("unroll") for (int k = 0; k < 2; ++k) dst[n][k] = *(const PG8_LAS bf16x8*)(lds + PG8_SB(b, h) + boff + n * 2048 + k * 1024); } while (0)
; template <class Epi, class Sched, bool ALIGN_EPI, bool F8 = false>
; __device__ __forceinline__ void gemm_phase(PG8_LAS unsigned char* lds, const Gemm g, const Sched& S, const Epi& E, const int wid) {
;     ...
;         for (int t = 0; t < nt; t += 2) {
;             const bool last = (t == nt - 2);
;             const char* a1 = cA + (size_t)(t + 1) * kstep;
;             const char* a2 = last ? nA : cA + (size_t)(t + 2) * kstep; const char* b2 = last ? nB : cB + (size_t)(t + 2) * kstep;
;             const char* a3 = a2 + kstep; const char* b3 = b2 + kstep;
;             PG8_LDB(B0, 0, 0); PG8_LDB(B1, 0, 1); PG8_SCHED; PG8_LDA(At, 0, 0); PG8_STAGE(PG8_SA(1, 1), a1 + hA, voffA);
;             PG8_WAIT_V(8); PG8_WAIT_L(0); PG8_BAR; PG8_MMA(0, 0, At, B0); PG8_MMA(0, 1, At, B1); PG8_BAR; PG8_SCHED;
;             PG8_LDA(At, 0, 1); PG8_STAGE(PG8_SB(0, 0), b2, voffB); PG8_STAGE(PG8_SB(0, 1), b2 + hB, voffB); PG8_STAGE(PG8_SA(0, 0), a2, voffA);
;             PG8_WAIT_V(8); PG8_WAIT_L(0); PG8_BAR; PG8_MMA(1, 0, At, B0); PG8_MMA(1, 1, At, B1); PG8_BAR; PG8_SCHED;
;             PG8_LDB(B0, 1, 0); PG8_LDB(B1, 1, 1); PG8_SCHED; PG8_LDA(At, 1, 0); PG8_STAGE(PG8_SA(0, 1), a2 + hA, voffA);
;             PG8_WAIT_V(8); PG8_WAIT_L(0); PG8_BAR; PG8_MMA(0, 0, At, B0); PG8_MMA(0, 1, At, B1); PG8_BAR; PG8_SCHED;
;             PG8_LDA(At, 1, 1); PG8_STAGE(PG8_SB(1, 0), b3, voffB); PG8_STAGE(PG8_SB(1, 1), b3 + hB, voffB); PG8_STAGE(PG8_SA(1, 0), a3, voffA);
;             PG8_WAIT_V(8); PG8_WAIT_L(0); PG8_BAR; PG8_MMA(1, 0, At, B0); PG8_MMA(1, 1, At, B1); PG8_BAR; PG8_SCHED;
;         }
	s_add_i32 s67, 0, 0x18000
	v_add_u32_e32 v135, s67, v133
	s_add_i32 s70, 0, 0x1c000
	ds_read_b128 v[136:139], v135
	ds_read_b128 v[140:143], v135 offset:1024
	ds_read_b128 v[144:147], v135 offset:2048
	ds_read_b128 v[148:151], v135 offset:3072
	v_add_u32_e32 v135, s70, v133
	ds_read_b128 v[152:155], v135
	ds_read_b128 v[156:159], v135 offset:1024
	ds_read_b128 v[160:163], v135 offset:2048
	ds_read_b128 v[164:167], v135 offset:3072
	s_add_u32 s68, s28, 0x80000
	s_mov_b32 m0, s50
	ds_read_b128 v[168:171], v134 offset:32768
	ds_read_b128 v[172:175], v134 offset:33792
	ds_read_b128 v[176:179], v134 offset:34816
	ds_read_b128 v[180:183], v134 offset:35840
	ds_read_b128 v[184:187], v134 offset:36864
	ds_read_b128 v[188:191], v134 offset:37888
	ds_read_b128 v[192:195], v134 offset:38912
	ds_read_b128 v[196:199], v134 offset:39936
	s_addc_u32 s69, s29, 0
	s_nop 0
	global_load_lds_dwordx4 v129, s[68:69]
	s_mov_b32 m0, s51
	s_nop 0
	global_load_lds_dwordx4 v132, s[68:69]
	s_waitcnt vmcnt(8)
	s_waitcnt lgkmcnt(0)
	s_barrier
	s_setprio 1
	s_waitcnt lgkmcnt(0)
	v_mfma_f32_16x16x32_bf16 v[120:123], v[136:139], v[168:171], v[120:123]
	v_mfma_f32_16x16x32_bf16 v[124:127], v[144:147], v[168:171], v[124:127]
	v_mfma_f32_16x16x32_bf16 v[108:111], v[136:139], v[176:179], v[108:111]
	v_mfma_f32_16x16x32_bf16 v[104:107], v[144:147], v[176:179], v[104:107]
	v_mfma_f32_16x16x32_bf16 v[92:95], v[136:139], v[184:187], v[92:95]
	v_mfma_f32_16x16x32_bf16 v[88:91], v[144:147], v[184:187], v[88:91]
	v_mfma_f32_16x16x32_bf16 v[76:79], v[136:139], v[192:195], v[76:79]
	v_mfma_f32_16x16x32_bf16 v[72:75], v[144:147], v[192:195], v[72:75]
	v_mfma_f32_16x16x32_bf16 v[120:123], v[140:143], v[172:175], v[120:123]
	v_mfma_f32_16x16x32_bf16 v[124:127], v[148:151], v[172:175], v[124:127]
	v_mfma_f32_16x16x32_bf16 v[108:111], v[140:143], v[180:183], v[108:111]
	v_mfma_f32_16x16x32_bf16 v[104:107], v[148:151], v[180:183], v[104:107]
	v_mfma_f32_16x16x32_bf16 v[92:95], v[140:143], v[188:191], v[92:95]
	v_mfma_f32_16x16x32_bf16 v[88:91], v[148:151], v[188:191], v[88:91]
	v_mfma_f32_16x16x32_bf16 v[76:79], v[140:143], v[196:199], v[76:79]
	v_mfma_f32_16x16x32_bf16 v[72:75], v[148:151], v[196:199], v[72:75]
	s_setprio 0
	s_setprio 1
	v_mfma_f32_16x16x32_bf16 v[116:119], v[152:155], v[168:171], v[116:119]
	v_mfma_f32_16x16x32_bf16 v[112:115], v[160:163], v[168:171], v[112:115]
	v_mfma_f32_16x16x32_bf16 v[100:103], v[152:155], v[176:179], v[100:103]
	v_mfma_f32_16x16x32_bf16 v[96:99], v[160:163], v[176:179], v[96:99]
	v_mfma_f32_16x16x32_bf16 v[84:87], v[152:155], v[184:187], v[84:87]
	v_mfma_f32_16x16x32_bf16 v[80:83], v[160:163], v[184:187], v[80:83]
	v_mfma_f32_16x16x32_bf16 v[60:63], v[152:155], v[192:195], v[60:63]
	v_mfma_f32_16x16x32_bf16 v[56:59], v[160:163], v[192:195], v[56:59]
	v_mfma_f32_16x16x32_bf16 v[116:119], v[156:159], v[172:175], v[116:119]
	v_mfma_f32_16x16x32_bf16 v[112:115], v[164:167], v[172:175], v[112:115]
	v_mfma_f32_16x16x32_bf16 v[100:103], v[156:159], v[180:183], v[100:103]
	v_mfma_f32_16x16x32_bf16 v[96:99], v[164:167], v[180:183], v[96:99]
	v_mfma_f32_16x16x32_bf16 v[84:87], v[156:159], v[188:191], v[84:87]
	v_mfma_f32_16x16x32_bf16 v[80:83], v[164:167], v[188:191], v[80:83]
	v_mfma_f32_16x16x32_bf16 v[60:63], v[156:159], v[196:199], v[60:63]
	v_mfma_f32_16x16x32_bf16 v[56:59], v[164:167], v[196:199], v[56:59]
	s_setprio 0
	s_barrier
	ds_read_b128 v[168:171], v134 offset:49152
	ds_read_b128 v[172:175], v134 offset:50176
	ds_read_b128 v[176:179], v134 offset:51200
	ds_read_b128 v[180:183], v134 offset:52224
	ds_read_b128 v[184:187], v134 offset:53248
	ds_read_b128 v[188:191], v134 offset:54272
	ds_read_b128 v[192:195], v134 offset:55296
	ds_read_b128 v[196:199], v134 offset:56320
	s_add_i32 s67, s67, s47
	s_add_u32 s100, s30, s2
	s_addc_u32 s101, s31, s3
	s_mov_b32 m0, s67
	s_nop 0
	global_load_lds_dwordx4 v130, s[100:101]
	s_add_i32 m0, s67, 0x2000
	s_add_u32 s100, s30, s2
	s_addc_u32 s101, s31, s3
	s_add_u32 s30, s30, 0x80080
	s_addc_u32 s31, s31, 0
	s_add_i32 s67, s70, s47
	global_load_lds_dwordx4 v131, s[100:101]
	s_mov_b32 m0, s67
	s_nop 0
	global_load_lds_dwordx4 v130, s[30:31]
	s_add_i32 m0, s67, 0x2000
	s_nop 0
	global_load_lds_dwordx4 v131, s[30:31]
	s_mov_b32 m0, s56
	s_add_u32 s100, s28, s2
	s_addc_u32 s101, s29, s3
	global_load_lds_dwordx4 v129, s[100:101]
	s_mov_b32 m0, s57
	s_add_u32 s100, s28, s2
	s_addc_u32 s101, s29, s3
	global_load_lds_dwordx4 v132, s[100:101]
	s_waitcnt vmcnt(8)
	s_waitcnt lgkmcnt(0)
	s_barrier
	s_setprio 1
	s_waitcnt lgkmcnt(0)
	v_mfma_f32_16x16x32_bf16 v[68:71], v[136:139], v[168:171], v[68:71]
	v_mfma_f32_16x16x32_bf16 v[64:67], v[144:147], v[168:171], v[64:67]
	v_mfma_f32_16x16x32_bf16 v[44:47], v[136:139], v[176:179], v[44:47]
	v_mfma_f32_16x16x32_bf16 v[40:43], v[144:147], v[176:179], v[40:43]
	v_mfma_f32_16x16x32_bf16 v[28:31], v[136:139], v[184:187], v[28:31]
	v_mfma_f32_16x16x32_bf16 v[24:27], v[144:147], v[184:187], v[24:27]
	v_mfma_f32_16x16x32_bf16 v[12:15], v[136:139], v[192:195], v[12:15]
	v_mfma_f32_16x16x32_bf16 v[8:11], v[144:147], v[192:195], v[8:11]
	v_mfma_f32_16x16x32_bf16 v[68:71], v[140:143], v[172:175], v[68:71]
	v_mfma_f32_16x16x32_bf16 v[64:67], v[148:151], v[172:175], v[64:67]
	v_mfma_f32_16x16x32_bf16 v[44:47], v[140:143], v[180:183], v[44:47]
	v_mfma_f32_16x16x32_bf16 v[40:43], v[148:151], v[180:183], v[40:43]
	v_mfma_f32_16x16x32_bf16 v[28:31], v[140:143], v[188:191], v[28:31]
	v_mfma_f32_16x16x32_bf16 v[24:27], v[148:151], v[188:191], v[24:27]
	v_mfma_f32_16x16x32_bf16 v[12:15], v[140:143], v[196:199], v[12:15]
	v_mfma_f32_16x16x32_bf16 v[8:11], v[148:151], v[196:199], v[8:11]
	s_setprio 0
	s_setprio 1
	v_mfma_f32_16x16x32_bf16 v[52:55], v[152:155], v[168:171], v[52:55]
	v_mfma_f32_16x16x32_bf16 v[48:51], v[160:163], v[168:171], v[48:51]
	v_mfma_f32_16x16x32_bf16 v[36:39], v[152:155], v[176:179], v[36:39]
	v_mfma_f32_16x16x32_bf16 v[32:35], v[160:163], v[176:179], v[32:35]
	v_mfma_f32_16x16x32_bf16 v[20:23], v[152:155], v[184:187], v[20:23]
	v_mfma_f32_16x16x32_bf16 v[16:19], v[160:163], v[184:187], v[16:19]
	v_mfma_f32_16x16x32_bf16 v[4:7], v[152:155], v[192:195], v[4:7]
	v_mfma_f32_16x16x32_bf16 v[0:3], v[160:163], v[192:195], v[0:3]
	v_mfma_f32_16x16x32_bf16 v[52:55], v[156:159], v[172:175], v[52:55]
	v_mfma_f32_16x16x32_bf16 v[48:51], v[164:167], v[172:175], v[48:51]
	v_mfma_f32_16x16x32_bf16 v[36:39], v[156:159], v[180:183], v[36:39]
	v_mfma_f32_16x16x32_bf16 v[32:35], v[164:167], v[180:183], v[32:35]
	v_mfma_f32_16x16x32_bf16 v[20:23], v[156:159], v[188:191], v[20:23]
	v_mfma_f32_16x16x32_bf16 v[16:19], v[164:167], v[188:191], v[16:19]
	v_mfma_f32_16x16x32_bf16 v[4:7], v[156:159], v[196:199], v[4:7]
	v_mfma_f32_16x16x32_bf16 v[0:3], v[164:167], v[196:199], v[0:3]
	s_setprio 0
	s_barrier
	s_add_u32 s26, s26, 0x100
	s_addc_u32 s27, s27, 0
	s_add_u32 s64, s64, 0x100
	s_addc_u32 s65, s65, 0
	s_cmp_ge_i32 s66, s52
	s_mov_b32 s28, s66
	s_cbranch_scc0 .LBB0_1990
	v_mov_b32_e32 v198, v204
